# v33 + the remaining FFN2 (and kv) K-loop MFMA blocks reordered (same-accumulator pairs adjacent) with the priority raise outside the barriers
# speedup vs baseline: 1.0006x; 1.0006x over previous
; #define PG8_STAGE(bufoff, gbase, voff) do { _Pragma("unroll") for (int _i = 0; _i < 2; ++_i) \
;         __builtin_amdgcn_global_load_lds((const unsigned*)((const char*)(gbase) + (voff)[_i]), (PG8_LAS unsigned*)(lds + (bufoff) + ldsw + _i * 8192), 16, 0, 0); } while (0)
; #define PG8_LDA(dst, b, h) do { _Pragma("unroll") for (int m = 0; m < 4; ++m) _Pragma("unroll") for (int k = 0; k < 2; ++k) dst[m][k] = *(const PG8_LAS bf16x8*)(lds + PG8_SA(b, h) + aoff + m * 2048 + k * 1024); } while (0)
; #define PG8_LDB(dst, b, h) do { _Pragma("unroll") for (int n = 0; n < 2; ++n) _Pragma("unroll") for (int k = 0; k < 2; ++k) dst[n][k] = *(const PG8_LAS bf16x8*)(lds + PG8_SB(b, h) + boff + n * 2048 + k * 1024); } while (0)
; #define PG8_MMA(ai, bj, At, Bt) do { __builtin_amdgcn_s_setprio(1); _Pragma("unroll") for (int m = 0; m < 4; ++m) _Pragma("unroll") for (int n = 0; n < 2; ++n) _Pragma("unroll") for (int k = 0; k < 2; ++k) \
;         acc[ai][bj][m][n] = __builtin_amdgcn_mfma_f32_16x16x32_bf16(Bt[n][k], At[m][k], acc[ai][bj][m][n], 0, 0, 0); __builtin_amdgcn_s_setprio(0); } while (0)
; #define PG8_WAIT_V(n) asm volatile("s_waitcnt vmcnt(" #n ")" ::: "memory")
; #define PG8_WAIT_L(n) asm volatile("s_waitcnt lgkmcnt(" #n ")" ::: "memory")
; #define PG8_BAR __builtin_amdgcn_s_barrier()
; #define PG8_SCHED __builtin_amdgcn_sched_barrier(0)
; template <class Epi, class Sched, bool ALIGN_EPI = false, bool SP2 = false, bool A_TILED = false>
; __device__ __forceinline__ void gemm_phase(PG8_LAS unsigned char* lds, const Gemm g, const Sched& S, const Epi& E) {
;     ...
;             PG8_LDB(B0, 0, 0); PG8_LDB(B1, 0, 1); PG8_SCHED; PG8_LDA(At, 0, 0); PG8_STAGE(PG8_SA(1, 1), a1 + hstepA, voffA);
;             PG8_WAIT_V(8); PG8_WAIT_L(0); PG8_BAR; PG8_MMA(0, 0, At, B0); PG8_MMA(0, 1, At, B1); PG8_BAR; PG8_SCHED;
;             PG8_LDA(At, 0, 1); PG8_STAGE(PG8_SB(0, 0), b2, voffB); PG8_STAGE(PG8_SB(0, 1), b2 + hstepB, voffB); PG8_STAGE(PG8_SA(0, 0), a2, voffA);
.LBB0_873:
	ds_read_b128 v[154:157], v1
	ds_read_b128 v[158:161], v1 offset:1024
	ds_read_b128 v[162:165], v1 offset:2048
	ds_read_b128 v[166:169], v1 offset:3072
	ds_read_b128 v[170:173], v146
	ds_read_b128 v[174:177], v146 offset:1024
	ds_read_b128 v[178:181], v146 offset:2048
	ds_read_b128 v[182:185], v146 offset:3072
	s_add_u32 s36, s34, 0xfffe0080
	s_addc_u32 s37, s35, -1
	s_cmp_eq_u32 s75, 4
	s_cselect_b32 s39, s27, s37
	s_cselect_b32 s38, s71, s36
	s_cselect_b32 s37, s25, s74
	s_cselect_b32 s36, s72, s73
	v_lshl_add_u64 v[218:219], s[34:35], 0, v[138:139]
	s_add_i32 m0, s23, 0xc000
	ds_read_b128 v[186:189], v147
	ds_read_b128 v[190:193], v147 offset:1024
	ds_read_b128 v[194:197], v147 offset:2048
	ds_read_b128 v[198:201], v147 offset:3072
	ds_read_b128 v[202:205], v147 offset:4096
	ds_read_b128 v[206:209], v147 offset:5120
	ds_read_b128 v[210:213], v147 offset:6144
	ds_read_b128 v[214:217], v147 offset:7168
	global_load_lds_dwordx4 v[218:219], off
	v_lshl_add_u64 v[218:219], s[34:35], 0, v[140:141]
	s_add_i32 m0, s23, 0xe000
	s_nop 0
	global_load_lds_dwordx4 v[218:219], off
	s_waitcnt vmcnt(8)
	s_waitcnt lgkmcnt(0)
	s_setprio 1
	s_barrier
	v_mfma_f32_16x16x32_bf16 v[126:129], v[154:157], v[186:189], v[126:129]
	v_mfma_f32_16x16x32_bf16 v[126:129], v[158:161], v[190:193], v[126:129]
	v_mfma_f32_16x16x32_bf16 v[122:125], v[162:165], v[186:189], v[122:125]
	v_mfma_f32_16x16x32_bf16 v[122:125], v[166:169], v[190:193], v[122:125]
	v_mfma_f32_16x16x32_bf16 v[118:121], v[154:157], v[194:197], v[118:121]
	v_mfma_f32_16x16x32_bf16 v[118:121], v[158:161], v[198:201], v[118:121]
	v_mfma_f32_16x16x32_bf16 v[114:117], v[162:165], v[194:197], v[114:117]
	v_mfma_f32_16x16x32_bf16 v[114:117], v[166:169], v[198:201], v[114:117]
	v_mfma_f32_16x16x32_bf16 v[102:105], v[154:157], v[202:205], v[102:105]
	v_mfma_f32_16x16x32_bf16 v[102:105], v[158:161], v[206:209], v[102:105]
	v_mfma_f32_16x16x32_bf16 v[98:101], v[162:165], v[202:205], v[98:101]
	v_mfma_f32_16x16x32_bf16 v[98:101], v[166:169], v[206:209], v[98:101]
	v_mfma_f32_16x16x32_bf16 v[86:89], v[154:157], v[210:213], v[86:89]
	v_mfma_f32_16x16x32_bf16 v[86:89], v[158:161], v[214:217], v[86:89]
	v_mfma_f32_16x16x32_bf16 v[82:85], v[162:165], v[210:213], v[82:85]
	v_mfma_f32_16x16x32_bf16 v[82:85], v[166:169], v[214:217], v[82:85]
	v_mfma_f32_16x16x32_bf16 v[110:113], v[170:173], v[186:189], v[110:113]
	v_mfma_f32_16x16x32_bf16 v[110:113], v[174:177], v[190:193], v[110:113]
	v_mfma_f32_16x16x32_bf16 v[106:109], v[178:181], v[186:189], v[106:109]
	v_mfma_f32_16x16x32_bf16 v[106:109], v[182:185], v[190:193], v[106:109]
	v_mfma_f32_16x16x32_bf16 v[94:97], v[170:173], v[194:197], v[94:97]
	v_mfma_f32_16x16x32_bf16 v[94:97], v[174:177], v[198:201], v[94:97]
	v_mfma_f32_16x16x32_bf16 v[90:93], v[178:181], v[194:197], v[90:93]
	v_mfma_f32_16x16x32_bf16 v[90:93], v[182:185], v[198:201], v[90:93]
	v_mfma_f32_16x16x32_bf16 v[78:81], v[170:173], v[202:205], v[78:81]
	v_mfma_f32_16x16x32_bf16 v[78:81], v[174:177], v[206:209], v[78:81]
	v_mfma_f32_16x16x32_bf16 v[74:77], v[178:181], v[202:205], v[74:77]
	v_mfma_f32_16x16x32_bf16 v[74:77], v[182:185], v[206:209], v[74:77]
	v_mfma_f32_16x16x32_bf16 v[70:73], v[170:173], v[210:213], v[70:73]
	v_mfma_f32_16x16x32_bf16 v[70:73], v[174:177], v[214:217], v[70:73]
	v_mfma_f32_16x16x32_bf16 v[66:69], v[178:181], v[210:213], v[66:69]
	v_mfma_f32_16x16x32_bf16 v[66:69], v[182:185], v[214:217], v[66:69]
	s_barrier
	s_setprio 0
	s_add_i32 s76, s59, s43
	v_lshl_add_u64 v[218:219], s[36:37], 0, v[130:131]
	s_mov_b32 m0, s76
	ds_read_b128 v[186:189], v147 offset:16384
	ds_read_b128 v[190:193], v147 offset:17408
	ds_read_b128 v[194:197], v147 offset:18432
	ds_read_b128 v[198:201], v147 offset:19456
	ds_read_b128 v[202:205], v147 offset:20480
	ds_read_b128 v[206:209], v147 offset:21504
	ds_read_b128 v[210:213], v147 offset:22528
	ds_read_b128 v[214:217], v147 offset:23552
	global_load_lds_dwordx4 v[218:219], off
	s_add_i32 m0, s76, 0x2000
	s_add_u32 s76, s36, 0x4000
	v_lshl_add_u64 v[218:219], s[36:37], 0, v[132:133]
	s_addc_u32 s77, s37, 0
	s_add_i32 s80, s60, s43
	global_load_lds_dwordx4 v[218:219], off
	v_lshl_add_u64 v[218:219], s[76:77], 0, v[130:131]
	s_mov_b32 m0, s80
	v_lshl_add_u64 v[220:221], s[38:39], 0, v[136:137]
	global_load_lds_dwordx4 v[218:219], off
	v_lshl_add_u64 v[218:219], s[76:77], 0, v[132:133]
	s_add_i32 m0, s80, 0x2000
	s_nop 0
	global_load_lds_dwordx4 v[218:219], off
	v_lshl_add_u64 v[218:219], s[38:39], 0, v[134:135]
	s_mov_b32 m0, s23
	s_nop 0
	global_load_lds_dwordx4 v[218:219], off
	s_mov_b32 m0, s44
	s_nop 0
	global_load_lds_dwordx4 v[220:221], off
	s_waitcnt vmcnt(8)
	s_waitcnt lgkmcnt(0)
	s_setprio 1
	s_barrier
; #define PG8_STAGE(bufoff, gbase, voff) do { _Pragma("unroll") for (int _i = 0; _i < 2; ++_i) \
;         __builtin_amdgcn_global_load_lds((const unsigned*)((const char*)(gbase) + (voff)[_i]), (PG8_LAS unsigned*)(lds + (bufoff) + ldsw + _i * 8192), 16, 0, 0); } while (0)
; #define PG8_LDA(dst, b, h) do { _Pragma("unroll") for (int m = 0; m < 4; ++m) _Pragma("unroll") for (int k = 0; k < 2; ++k) dst[m][k] = *(const PG8_LAS bf16x8*)(lds + PG8_SA(b, h) + aoff + m * 2048 + k * 1024); } while (0)
; #define PG8_LDB(dst, b, h) do { _Pragma("unroll") for (int n = 0; n < 2; ++n) _Pragma("unroll") for (int k = 0; k < 2; ++k) dst[n][k] = *(const PG8_LAS bf16x8*)(lds + PG8_SB(b, h) + boff + n * 2048 + k * 1024); } while (0)
; #define PG8_MMA(ai, bj, At, Bt) do { __builtin_amdgcn_s_setprio(1); _Pragma("unroll") for (int m = 0; m < 4; ++m) _Pragma("unroll") for (int n = 0; n < 2; ++n) _Pragma("unroll") for (int k = 0; k < 2; ++k) \
;         acc[ai][bj][m][n] = __builtin_amdgcn_mfma_f32_16x16x32_bf16(Bt[n][k], At[m][k], acc[ai][bj][m][n], 0, 0, 0); __builtin_amdgcn_s_setprio(0); } while (0)
; #define PG8_WAIT_V(n) asm volatile("s_waitcnt vmcnt(" #n ")" ::: "memory")
; #define PG8_WAIT_L(n) asm volatile("s_waitcnt lgkmcnt(" #n ")" ::: "memory")
; #define PG8_BAR __builtin_amdgcn_s_barrier()
; #define PG8_SCHED __builtin_amdgcn_sched_barrier(0)
; template <class Epi, class Sched, bool ALIGN_EPI = false, bool SP2 = false, bool A_TILED = false>
; __device__ __forceinline__ void gemm_phase(PG8_LAS unsigned char* lds, const Gemm g, const Sched& S, const Epi& E) {
;     ...
;             PG8_WAIT_V(8); PG8_WAIT_L(0); PG8_BAR; PG8_MMA(1, 0, At, B0); PG8_MMA(1, 1, At, B1); PG8_BAR; PG8_SCHED;
;             PG8_LDB(B0, 1, 0); PG8_LDB(B1, 1, 1); PG8_SCHED; PG8_LDA(At, 1, 0); PG8_STAGE(PG8_SA(0, 1), a2 + hstepA, voffA);
;             PG8_WAIT_V(8); PG8_WAIT_L(0); PG8_BAR; PG8_MMA(0, 0, At, B0); PG8_MMA(0, 1, At, B1); PG8_BAR; PG8_SCHED;
	v_mfma_f32_16x16x32_bf16 v[62:65], v[154:157], v[186:189], v[62:65]
	v_mfma_f32_16x16x32_bf16 v[62:65], v[158:161], v[190:193], v[62:65]
	v_mfma_f32_16x16x32_bf16 v[58:61], v[162:165], v[186:189], v[58:61]
	v_mfma_f32_16x16x32_bf16 v[58:61], v[166:169], v[190:193], v[58:61]
	v_mfma_f32_16x16x32_bf16 v[46:49], v[170:173], v[186:189], v[46:49]
	v_mfma_f32_16x16x32_bf16 v[46:49], v[174:177], v[190:193], v[46:49]
	v_mfma_f32_16x16x32_bf16 v[42:45], v[178:181], v[186:189], v[42:45]
	v_mfma_f32_16x16x32_bf16 v[42:45], v[182:185], v[190:193], v[42:45]
	v_mfma_f32_16x16x32_bf16 v[54:57], v[154:157], v[194:197], v[54:57]
	v_mfma_f32_16x16x32_bf16 v[54:57], v[158:161], v[198:201], v[54:57]
	v_mfma_f32_16x16x32_bf16 v[50:53], v[162:165], v[194:197], v[50:53]
	v_mfma_f32_16x16x32_bf16 v[50:53], v[166:169], v[198:201], v[50:53]
	v_mfma_f32_16x16x32_bf16 v[30:33], v[170:173], v[194:197], v[30:33]
	v_mfma_f32_16x16x32_bf16 v[30:33], v[174:177], v[198:201], v[30:33]
	v_mfma_f32_16x16x32_bf16 v[26:29], v[178:181], v[194:197], v[26:29]
	v_mfma_f32_16x16x32_bf16 v[26:29], v[182:185], v[198:201], v[26:29]
	v_mfma_f32_16x16x32_bf16 v[38:41], v[154:157], v[202:205], v[38:41]
	v_mfma_f32_16x16x32_bf16 v[38:41], v[158:161], v[206:209], v[38:41]
	v_mfma_f32_16x16x32_bf16 v[34:37], v[162:165], v[202:205], v[34:37]
	v_mfma_f32_16x16x32_bf16 v[34:37], v[166:169], v[206:209], v[34:37]
	v_mfma_f32_16x16x32_bf16 v[14:17], v[170:173], v[202:205], v[14:17]
	v_mfma_f32_16x16x32_bf16 v[14:17], v[174:177], v[206:209], v[14:17]
	v_mfma_f32_16x16x32_bf16 v[10:13], v[178:181], v[202:205], v[10:13]
	v_mfma_f32_16x16x32_bf16 v[10:13], v[182:185], v[206:209], v[10:13]
	v_mfma_f32_16x16x32_bf16 v[22:25], v[154:157], v[210:213], v[22:25]
	v_mfma_f32_16x16x32_bf16 v[22:25], v[158:161], v[214:217], v[22:25]
	v_mfma_f32_16x16x32_bf16 v[18:21], v[162:165], v[210:213], v[18:21]
	v_mfma_f32_16x16x32_bf16 v[18:21], v[166:169], v[214:217], v[18:21]
	v_mfma_f32_16x16x32_bf16 v[6:9], v[170:173], v[210:213], v[6:9]
	v_mfma_f32_16x16x32_bf16 v[6:9], v[174:177], v[214:217], v[6:9]
	v_mfma_f32_16x16x32_bf16 v[2:5], v[178:181], v[210:213], v[2:5]
	v_mfma_f32_16x16x32_bf16 v[2:5], v[182:185], v[214:217], v[2:5]
	s_barrier
	s_setprio 0
	s_add_i32 s76, 0, 0x18000
	v_add_u32_e32 v148, s76, v150
	s_add_i32 s77, 0, 0x1c000
	ds_read_b128 v[154:157], v148
	ds_read_b128 v[158:161], v148 offset:1024
	ds_read_b128 v[162:165], v148 offset:2048
	ds_read_b128 v[166:169], v148 offset:3072
	v_add_u32_e32 v148, s77, v150
	ds_read_b128 v[170:173], v148
	ds_read_b128 v[174:177], v148 offset:1024
	ds_read_b128 v[178:181], v148 offset:2048
	ds_read_b128 v[182:185], v148 offset:3072
	s_add_u32 s38, s38, 0x20000
	s_addc_u32 s39, s39, 0
	s_mov_b32 m0, s45
	v_lshl_add_u64 v[222:223], s[38:39], 0, v[134:135]
	ds_read_b128 v[186:189], v147 offset:32768
	ds_read_b128 v[190:193], v147 offset:33792
	ds_read_b128 v[194:197], v147 offset:34816
	ds_read_b128 v[198:201], v147 offset:35840
	ds_read_b128 v[202:205], v147 offset:36864
	ds_read_b128 v[206:209], v147 offset:37888
	ds_read_b128 v[210:213], v147 offset:38912
	ds_read_b128 v[214:217], v147 offset:39936
	global_load_lds_dwordx4 v[222:223], off
	v_lshl_add_u64 v[222:223], s[38:39], 0, v[136:137]
	s_mov_b32 m0, s54
	s_nop 0
	global_load_lds_dwordx4 v[222:223], off
	s_waitcnt vmcnt(8)
	s_waitcnt lgkmcnt(0)
	s_setprio 1
	s_barrier
	v_mfma_f32_16x16x32_bf16 v[126:129], v[154:157], v[186:189], v[126:129]
	v_mfma_f32_16x16x32_bf16 v[126:129], v[158:161], v[190:193], v[126:129]
	v_mfma_f32_16x16x32_bf16 v[122:125], v[162:165], v[186:189], v[122:125]
	v_mfma_f32_16x16x32_bf16 v[122:125], v[166:169], v[190:193], v[122:125]
	v_mfma_f32_16x16x32_bf16 v[110:113], v[170:173], v[186:189], v[110:113]
	v_mfma_f32_16x16x32_bf16 v[110:113], v[174:177], v[190:193], v[110:113]
	v_mfma_f32_16x16x32_bf16 v[106:109], v[178:181], v[186:189], v[106:109]
	v_mfma_f32_16x16x32_bf16 v[106:109], v[182:185], v[190:193], v[106:109]
	v_mfma_f32_16x16x32_bf16 v[118:121], v[154:157], v[194:197], v[118:121]
	v_mfma_f32_16x16x32_bf16 v[118:121], v[158:161], v[198:201], v[118:121]
	v_mfma_f32_16x16x32_bf16 v[114:117], v[162:165], v[194:197], v[114:117]
	v_mfma_f32_16x16x32_bf16 v[114:117], v[166:169], v[198:201], v[114:117]
	v_mfma_f32_16x16x32_bf16 v[94:97], v[170:173], v[194:197], v[94:97]
	v_mfma_f32_16x16x32_bf16 v[94:97], v[174:177], v[198:201], v[94:97]
	v_mfma_f32_16x16x32_bf16 v[90:93], v[178:181], v[194:197], v[90:93]
	v_mfma_f32_16x16x32_bf16 v[90:93], v[182:185], v[198:201], v[90:93]
	v_mfma_f32_16x16x32_bf16 v[102:105], v[154:157], v[202:205], v[102:105]
	v_mfma_f32_16x16x32_bf16 v[102:105], v[158:161], v[206:209], v[102:105]
	v_mfma_f32_16x16x32_bf16 v[98:101], v[162:165], v[202:205], v[98:101]
	v_mfma_f32_16x16x32_bf16 v[98:101], v[166:169], v[206:209], v[98:101]
	v_mfma_f32_16x16x32_bf16 v[78:81], v[170:173], v[202:205], v[78:81]
	v_mfma_f32_16x16x32_bf16 v[78:81], v[174:177], v[206:209], v[78:81]
	v_mfma_f32_16x16x32_bf16 v[74:77], v[178:181], v[202:205], v[74:77]
	v_mfma_f32_16x16x32_bf16 v[74:77], v[182:185], v[206:209], v[74:77]
	v_mfma_f32_16x16x32_bf16 v[86:89], v[154:157], v[210:213], v[86:89]
	v_mfma_f32_16x16x32_bf16 v[86:89], v[158:161], v[214:217], v[86:89]
	v_mfma_f32_16x16x32_bf16 v[82:85], v[162:165], v[210:213], v[82:85]
	v_mfma_f32_16x16x32_bf16 v[82:85], v[166:169], v[214:217], v[82:85]
	v_mfma_f32_16x16x32_bf16 v[70:73], v[170:173], v[210:213], v[70:73]
	v_mfma_f32_16x16x32_bf16 v[70:73], v[174:177], v[214:217], v[70:73]
	v_mfma_f32_16x16x32_bf16 v[66:69], v[178:181], v[210:213], v[66:69]
	v_mfma_f32_16x16x32_bf16 v[66:69], v[182:185], v[214:217], v[66:69]
	s_barrier
; #define PG8_STAGE(bufoff, gbase, voff) do { _Pragma("unroll") for (int _i = 0; _i < 2; ++_i) \
;         __builtin_amdgcn_global_load_lds((const unsigned*)((const char*)(gbase) + (voff)[_i]), (PG8_LAS unsigned*)(lds + (bufoff) + ldsw + _i * 8192), 16, 0, 0); } while (0)
; #define PG8_LDA(dst, b, h) do { _Pragma("unroll") for (int m = 0; m < 4; ++m) _Pragma("unroll") for (int k = 0; k < 2; ++k) dst[m][k] = *(const PG8_LAS bf16x8*)(lds + PG8_SA(b, h) + aoff + m * 2048 + k * 1024); } while (0)
; #define PG8_MMA(ai, bj, At, Bt) do { __builtin_amdgcn_s_setprio(1); _Pragma("unroll") for (int m = 0; m < 4; ++m) _Pragma("unroll") for (int n = 0; n < 2; ++n) _Pragma("unroll") for (int k = 0; k < 2; ++k) \
;         acc[ai][bj][m][n] = __builtin_amdgcn_mfma_f32_16x16x32_bf16(Bt[n][k], At[m][k], acc[ai][bj][m][n], 0, 0, 0); __builtin_amdgcn_s_setprio(0); } while (0)
; #define PG8_WAIT_V(n) asm volatile("s_waitcnt vmcnt(" #n ")" ::: "memory")
; #define PG8_WAIT_L(n) asm volatile("s_waitcnt lgkmcnt(" #n ")" ::: "memory")
; #define PG8_BAR __builtin_amdgcn_s_barrier()
; #define PG8_SCHED __builtin_amdgcn_sched_barrier(0)
; template <class Epi, class Sched, bool ALIGN_EPI = false, bool SP2 = false, bool A_TILED = false>
; __device__ __forceinline__ void gemm_phase(PG8_LAS unsigned char* lds, const Gemm g, const Sched& S, const Epi& E) {
;     ...
;             PG8_LDA(At, 1, 1); PG8_STAGE(PG8_SB(1, 0), b3, voffB); PG8_STAGE(PG8_SB(1, 1), b3 + hstepB, voffB); PG8_STAGE(PG8_SA(1, 0), a3, voffA);
;             PG8_WAIT_V(8); PG8_WAIT_L(0); PG8_BAR; PG8_MMA(1, 0, At, B0); PG8_MMA(1, 1, At, B1); PG8_BAR; PG8_SCHED;
	s_setprio 0
	s_add_u32 s38, s36, 0x8000
	s_addc_u32 s39, s37, 0
	s_add_i32 s76, s76, s43
	v_lshl_add_u64 v[222:223], s[38:39], 0, v[130:131]
	s_mov_b32 m0, s76
	ds_read_b128 v[186:189], v147 offset:49152
	ds_read_b128 v[190:193], v147 offset:50176
	ds_read_b128 v[194:197], v147 offset:51200
	ds_read_b128 v[198:201], v147 offset:52224
	ds_read_b128 v[202:205], v147 offset:53248
	ds_read_b128 v[206:209], v147 offset:54272
	ds_read_b128 v[210:213], v147 offset:55296
	ds_read_b128 v[214:217], v147 offset:56320
	global_load_lds_dwordx4 v[222:223], off
	s_add_i32 m0, s76, 0x2000
	s_add_u32 s36, s36, 0xc000
	v_lshl_add_u64 v[222:223], s[38:39], 0, v[132:133]
	s_addc_u32 s37, s37, 0
	s_add_i32 s38, s77, s43
	global_load_lds_dwordx4 v[222:223], off
	v_lshl_add_u64 v[222:223], s[36:37], 0, v[130:131]
	s_mov_b32 m0, s38
	v_lshl_add_u64 v[218:219], v[218:219], 0, s[10:11]
	global_load_lds_dwordx4 v[222:223], off
	v_lshl_add_u64 v[222:223], s[36:37], 0, v[132:133]
	s_add_i32 m0, s38, 0x2000
	s_nop 0
	global_load_lds_dwordx4 v[222:223], off
	s_mov_b32 m0, s56
	s_nop 0
	global_load_lds_dwordx4 v[218:219], off
	v_lshl_add_u64 v[218:219], v[220:221], 0, s[10:11]
	s_mov_b32 m0, s57
	s_nop 0
	global_load_lds_dwordx4 v[218:219], off
	s_waitcnt vmcnt(8)
	s_waitcnt lgkmcnt(0)
	s_setprio 1
	s_barrier
	v_mfma_f32_16x16x32_bf16 v[62:65], v[154:157], v[186:189], v[62:65]
	v_mfma_f32_16x16x32_bf16 v[62:65], v[158:161], v[190:193], v[62:65]
	v_mfma_f32_16x16x32_bf16 v[58:61], v[162:165], v[186:189], v[58:61]
	v_mfma_f32_16x16x32_bf16 v[58:61], v[166:169], v[190:193], v[58:61]
	v_mfma_f32_16x16x32_bf16 v[46:49], v[170:173], v[186:189], v[46:49]
	v_mfma_f32_16x16x32_bf16 v[46:49], v[174:177], v[190:193], v[46:49]
	v_mfma_f32_16x16x32_bf16 v[42:45], v[178:181], v[186:189], v[42:45]
	v_mfma_f32_16x16x32_bf16 v[42:45], v[182:185], v[190:193], v[42:45]
	v_mfma_f32_16x16x32_bf16 v[54:57], v[154:157], v[194:197], v[54:57]
	v_mfma_f32_16x16x32_bf16 v[54:57], v[158:161], v[198:201], v[54:57]
	v_mfma_f32_16x16x32_bf16 v[50:53], v[162:165], v[194:197], v[50:53]
	v_mfma_f32_16x16x32_bf16 v[50:53], v[166:169], v[198:201], v[50:53]
	v_mfma_f32_16x16x32_bf16 v[30:33], v[170:173], v[194:197], v[30:33]
	v_mfma_f32_16x16x32_bf16 v[30:33], v[174:177], v[198:201], v[30:33]
	v_mfma_f32_16x16x32_bf16 v[26:29], v[178:181], v[194:197], v[26:29]
	v_mfma_f32_16x16x32_bf16 v[26:29], v[182:185], v[198:201], v[26:29]
	v_mfma_f32_16x16x32_bf16 v[38:41], v[154:157], v[202:205], v[38:41]
	v_mfma_f32_16x16x32_bf16 v[38:41], v[158:161], v[206:209], v[38:41]
	v_mfma_f32_16x16x32_bf16 v[34:37], v[162:165], v[202:205], v[34:37]
	v_mfma_f32_16x16x32_bf16 v[34:37], v[166:169], v[206:209], v[34:37]
	v_mfma_f32_16x16x32_bf16 v[14:17], v[170:173], v[202:205], v[14:17]
	v_mfma_f32_16x16x32_bf16 v[14:17], v[174:177], v[206:209], v[14:17]
	v_mfma_f32_16x16x32_bf16 v[10:13], v[178:181], v[202:205], v[10:13]
	v_mfma_f32_16x16x32_bf16 v[10:13], v[182:185], v[206:209], v[10:13]
	v_mfma_f32_16x16x32_bf16 v[22:25], v[154:157], v[210:213], v[22:25]
	v_mfma_f32_16x16x32_bf16 v[22:25], v[158:161], v[214:217], v[22:25]
	v_mfma_f32_16x16x32_bf16 v[18:21], v[162:165], v[210:213], v[18:21]
	v_mfma_f32_16x16x32_bf16 v[18:21], v[166:169], v[214:217], v[18:21]
	v_mfma_f32_16x16x32_bf16 v[6:9], v[170:173], v[210:213], v[6:9]
	v_mfma_f32_16x16x32_bf16 v[6:9], v[174:177], v[214:217], v[6:9]
	v_mfma_f32_16x16x32_bf16 v[2:5], v[178:181], v[210:213], v[2:5]
	v_mfma_f32_16x16x32_bf16 v[2:5], v[182:185], v[214:217], v[2:5]
	s_barrier
	s_setprio 0
	s_add_i32 s75, s75, 2
	s_add_u32 s73, s73, 0x10000
	s_addc_u32 s74, s74, 0
	s_add_u32 s34, s34, 0x100
	s_addc_u32 s35, s35, 0
	s_cmp_gt_u32 s75, 5
	s_cbranch_scc0 .LBB0_873
	s_and_b64 vcc, exec, s[12:13]
	s_cbranch_vccz .LBB0_876
	s_barrier

; #define PG8_STAGE(bufoff, gbase, voff) do { _Pragma("unroll") for (int _i = 0; _i < 2; ++_i) \
;         __builtin_amdgcn_global_load_lds((const unsigned*)((const char*)(gbase) + (voff)[_i]), (PG8_LAS unsigned*)(lds + (bufoff) + ldsw + _i * 8192), 16, 0, 0); } while (0)
; #define PG8_LDA(dst, b, h) do { _Pragma("unroll") for (int m = 0; m < 4; ++m) _Pragma("unroll") for (int k = 0; k < 2; ++k) dst[m][k] = *(const PG8_LAS bf16x8*)(lds + PG8_SA(b, h) + aoff + m * 2048 + k * 1024); } while (0)
; #define PG8_LDB(dst, b, h) do { _Pragma("unroll") for (int n = 0; n < 2; ++n) _Pragma("unroll") for (int k = 0; k < 2; ++k) dst[n][k] = *(const PG8_LAS bf16x8*)(lds + PG8_SB(b, h) + boff + n * 2048 + k * 1024); } while (0)
; #define PG8_WAIT_V(n) asm volatile("s_waitcnt vmcnt(" #n ")" ::: "memory")
; #define PG8_WAIT_L(n) asm volatile("s_waitcnt lgkmcnt(" #n ")" ::: "memory")
; #define PG8_BAR __builtin_amdgcn_s_barrier()
; #define PG8_SCHED __builtin_amdgcn_sched_barrier(0)
; template <class Epi, class Sched, bool ALIGN_EPI = false, bool SP2 = false, bool A_TILED = false>
; __device__ __forceinline__ void gemm_phase(PG8_LAS unsigned char* lds, const Gemm g, const Sched& S, const Epi& E) {
;     ...
;         for (int t = 0; t < nt; t += 2) {
;             const bool last = (t == nt - 2);
;             const char* a1 = cA + (size_t)(t + 1) * kstepA;
;             const char* a2 = last ? nA : cA + (size_t)(t + 2) * kstepA; const char* b2 = last ? nB : cB + (size_t)(t + 2) * kstepB;
;             const char* a3 = a2 + kstepA; const char* b3 = b2 + kstepB;
;             if (last && has_next) S.a_ready(nxt);
;             if constexpr (SP2) {
;             PG8_LDB(B0, 0, 0); PG8_LDB(B1, 0, 1); PG8_SCHED; PG8_LDA(At, 0, 0); PG8_STAGE(PG8_SA(1, 1), a1 + hstepA, voffA);
;             PG8_WAIT_V(8); PG8_WAIT_L(0); PG8_BAR; PG8_MMA(0, 0, At, B0); PG8_MMA(0, 1, At, B1); PG8_BAR; PG8_SCHED;
;             PG8_LDA(At, 0, 1); PG8_STAGE(PG8_SB(0, 0), b2, voffB); PG8_STAGE(PG8_SB(0, 1), b2 + hstepB, voffB); PG8_STAGE(PG8_SA(0, 0), a2, voffA);
;             PG8_WAIT_V(8); PG8_WAIT_L(0); PG8_BAR; PG8_MMA(1, 0, At, B0); PG8_MMA(1, 1, At, B1); PG8_BAR; PG8_SCHED;
;             PG8_LDB(B0, 1, 0); PG8_LDB(B1, 1, 1); PG8_SCHED; PG8_LDA(At, 1, 0); PG8_STAGE(PG8_SA(0, 1), a2 + hstepA, voffA);
.LBB0_1103:
	ds_read_b128 v[130:133], v197
	ds_read_b128 v[134:137], v197 offset:1024
	ds_read_b128 v[138:141], v197 offset:2048
	ds_read_b128 v[142:145], v197 offset:3072
	ds_read_b128 v[146:149], v237
	ds_read_b128 v[150:153], v237 offset:1024
	ds_read_b128 v[154:157], v237 offset:2048
	ds_read_b128 v[158:161], v237 offset:3072
	s_add_u32 s40, s38, 0xfff00080
	s_addc_u32 s41, s39, -1
	s_cmp_eq_u32 s72, 60
	s_cselect_b32 s43, s29, s41
	s_cselect_b32 s42, s37, s40
	s_cselect_b32 s41, s27, s71
	s_cselect_b32 s40, s69, s70
	v_lshl_add_u64 v[228:229], s[38:39], 0, v[214:215]
	s_add_i32 m0, s55, 0xc000
	ds_read_b128 v[162:165], v238
	ds_read_b128 v[166:169], v238 offset:1024
	ds_read_b128 v[170:173], v238 offset:2048
	ds_read_b128 v[174:177], v238 offset:3072
	ds_read_b128 v[178:181], v238 offset:4096
	ds_read_b128 v[182:185], v238 offset:5120
	ds_read_b128 v[220:223], v238 offset:6144
	ds_read_b128 v[224:227], v238 offset:7168
	global_load_lds_dwordx4 v[228:229], off
	v_lshl_add_u64 v[228:229], s[38:39], 0, v[216:217]
	s_add_i32 m0, s55, 0xe000
	s_nop 0
	global_load_lds_dwordx4 v[228:229], off
	s_waitcnt vmcnt(8)
	s_waitcnt lgkmcnt(0)
	s_setprio 1
	s_barrier
	v_mfma_f32_16x16x32_bf16 v[90:93], v[130:133], v[162:165], v[90:93]
	v_mfma_f32_16x16x32_bf16 v[90:93], v[134:137], v[166:169], v[90:93]
	v_mfma_f32_16x16x32_bf16 v[98:101], v[138:141], v[162:165], v[98:101]
	v_mfma_f32_16x16x32_bf16 v[98:101], v[142:145], v[166:169], v[98:101]
	v_mfma_f32_16x16x32_bf16 v[122:125], v[130:133], v[170:173], v[122:125]
	v_mfma_f32_16x16x32_bf16 v[122:125], v[134:137], v[174:177], v[122:125]
	v_mfma_f32_16x16x32_bf16 v[126:129], v[138:141], v[170:173], v[126:129]
	v_mfma_f32_16x16x32_bf16 v[126:129], v[142:145], v[174:177], v[126:129]
	v_mfma_f32_16x16x32_bf16 v[102:105], v[130:133], v[178:181], v[102:105]
	v_mfma_f32_16x16x32_bf16 v[102:105], v[134:137], v[182:185], v[102:105]
	v_mfma_f32_16x16x32_bf16 v[94:97], v[138:141], v[178:181], v[94:97]
	v_mfma_f32_16x16x32_bf16 v[94:97], v[142:145], v[182:185], v[94:97]
	v_mfma_f32_16x16x32_bf16 v[78:81], v[130:133], v[220:223], v[78:81]
	v_mfma_f32_16x16x32_bf16 v[78:81], v[134:137], v[224:227], v[78:81]
	v_mfma_f32_16x16x32_bf16 v[74:77], v[138:141], v[220:223], v[74:77]
	v_mfma_f32_16x16x32_bf16 v[74:77], v[142:145], v[224:227], v[74:77]
	v_mfma_f32_16x16x32_bf16 v[106:109], v[146:149], v[162:165], v[106:109]
	v_mfma_f32_16x16x32_bf16 v[106:109], v[150:153], v[166:169], v[106:109]
	v_mfma_f32_16x16x32_bf16 v[114:117], v[154:157], v[162:165], v[114:117]
	v_mfma_f32_16x16x32_bf16 v[114:117], v[158:161], v[166:169], v[114:117]
	v_mfma_f32_16x16x32_bf16 v[118:121], v[146:149], v[170:173], v[118:121]
	v_mfma_f32_16x16x32_bf16 v[118:121], v[150:153], v[174:177], v[118:121]
	v_mfma_f32_16x16x32_bf16 v[110:113], v[154:157], v[170:173], v[110:113]
	v_mfma_f32_16x16x32_bf16 v[110:113], v[158:161], v[174:177], v[110:113]
	v_mfma_f32_16x16x32_bf16 v[86:89], v[146:149], v[178:181], v[86:89]
	v_mfma_f32_16x16x32_bf16 v[86:89], v[150:153], v[182:185], v[86:89]
	v_mfma_f32_16x16x32_bf16 v[82:85], v[154:157], v[178:181], v[82:85]
	v_mfma_f32_16x16x32_bf16 v[82:85], v[158:161], v[182:185], v[82:85]
	v_mfma_f32_16x16x32_bf16 v[70:73], v[146:149], v[220:223], v[70:73]
	v_mfma_f32_16x16x32_bf16 v[70:73], v[150:153], v[224:227], v[70:73]
	v_mfma_f32_16x16x32_bf16 v[66:69], v[154:157], v[220:223], v[66:69]
	v_mfma_f32_16x16x32_bf16 v[66:69], v[158:161], v[224:227], v[66:69]
	s_barrier
	s_setprio 0
	s_add_i32 s73, s66, s54
	v_lshl_add_u64 v[228:229], s[40:41], 0, v[188:189]
	s_mov_b32 m0, s73
	ds_read_b128 v[162:165], v238 offset:16384
	ds_read_b128 v[166:169], v238 offset:17408
	ds_read_b128 v[170:173], v238 offset:18432
	ds_read_b128 v[174:177], v238 offset:19456
	ds_read_b128 v[178:181], v238 offset:20480
	ds_read_b128 v[182:185], v238 offset:21504
	ds_read_b128 v[220:223], v238 offset:22528
	ds_read_b128 v[224:227], v238 offset:23552
	global_load_lds_dwordx4 v[228:229], off
	s_add_i32 m0, s73, 0x2000
	s_add_u32 s74, s40, 0x4000
	v_lshl_add_u64 v[228:229], s[40:41], 0, v[192:193]
	s_addc_u32 s75, s41, 0
	s_add_i32 s73, s67, s54
	global_load_lds_dwordx4 v[228:229], off
	v_lshl_add_u64 v[228:229], s[74:75], 0, v[188:189]
	s_mov_b32 m0, s73
	v_lshl_add_u64 v[230:231], s[42:43], 0, v[190:191]
	global_load_lds_dwordx4 v[228:229], off
	v_lshl_add_u64 v[228:229], s[74:75], 0, v[192:193]
	s_add_i32 m0, s73, 0x2000
	s_nop 0
	global_load_lds_dwordx4 v[228:229], off
	v_lshl_add_u64 v[228:229], s[42:43], 0, v[186:187]
	s_mov_b32 m0, s55
	s_nop 0
	global_load_lds_dwordx4 v[228:229], off
	s_mov_b32 m0, s56
	s_nop 0
	global_load_lds_dwordx4 v[230:231], off
	s_waitcnt vmcnt(8)
	s_waitcnt lgkmcnt(0)
	s_setprio 1
	s_barrier
; #define PG8_STAGE(bufoff, gbase, voff) do { _Pragma("unroll") for (int _i = 0; _i < 2; ++_i) \
;         __builtin_amdgcn_global_load_lds((const unsigned*)((const char*)(gbase) + (voff)[_i]), (PG8_LAS unsigned*)(lds + (bufoff) + ldsw + _i * 8192), 16, 0, 0); } while (0)
; #define PG8_LDA(dst, b, h) do { _Pragma("unroll") for (int m = 0; m < 4; ++m) _Pragma("unroll") for (int k = 0; k < 2; ++k) dst[m][k] = *(const PG8_LAS bf16x8*)(lds + PG8_SA(b, h) + aoff + m * 2048 + k * 1024); } while (0)
; #define PG8_LDB(dst, b, h) do { _Pragma("unroll") for (int n = 0; n < 2; ++n) _Pragma("unroll") for (int k = 0; k < 2; ++k) dst[n][k] = *(const PG8_LAS bf16x8*)(lds + PG8_SB(b, h) + boff + n * 2048 + k * 1024); } while (0)
; #define PG8_MMA(ai, bj, At, Bt) do { __builtin_amdgcn_s_setprio(1); _Pragma("unroll") for (int m = 0; m < 4; ++m) _Pragma("unroll") for (int n = 0; n < 2; ++n) _Pragma("unroll") for (int k = 0; k < 2; ++k) \
;         acc[ai][bj][m][n] = __builtin_amdgcn_mfma_f32_16x16x32_bf16(Bt[n][k], At[m][k], acc[ai][bj][m][n], 0, 0, 0); __builtin_amdgcn_s_setprio(0); } while (0)
; #define PG8_WAIT_V(n) asm volatile("s_waitcnt vmcnt(" #n ")" ::: "memory")
; #define PG8_WAIT_L(n) asm volatile("s_waitcnt lgkmcnt(" #n ")" ::: "memory")
; #define PG8_BAR __builtin_amdgcn_s_barrier()
; #define PG8_SCHED __builtin_amdgcn_sched_barrier(0)
; template <class Epi, class Sched, bool ALIGN_EPI = false, bool SP2 = false, bool A_TILED = false>
; __device__ __forceinline__ void gemm_phase(PG8_LAS unsigned char* lds, const Gemm g, const Sched& S, const Epi& E) {
;     ...
;             PG8_WAIT_V(8); PG8_WAIT_L(0); PG8_BAR; PG8_MMA(1, 0, At, B0); PG8_MMA(1, 1, At, B1); PG8_BAR; PG8_SCHED;
;             PG8_LDB(B0, 1, 0); PG8_LDB(B1, 1, 1); PG8_SCHED; PG8_LDA(At, 1, 0); PG8_STAGE(PG8_SA(0, 1), a2 + hstepA, voffA);
;             PG8_WAIT_V(8); PG8_WAIT_L(0); PG8_BAR; PG8_MMA(0, 0, At, B0); PG8_MMA(0, 1, At, B1); PG8_BAR; PG8_SCHED;
	v_mfma_f32_16x16x32_bf16 v[62:65], v[130:133], v[162:165], v[62:65]
	v_mfma_f32_16x16x32_bf16 v[62:65], v[134:137], v[166:169], v[62:65]
	v_mfma_f32_16x16x32_bf16 v[58:61], v[138:141], v[162:165], v[58:61]
	v_mfma_f32_16x16x32_bf16 v[58:61], v[142:145], v[166:169], v[58:61]
	v_mfma_f32_16x16x32_bf16 v[54:57], v[146:149], v[162:165], v[54:57]
	v_mfma_f32_16x16x32_bf16 v[54:57], v[150:153], v[166:169], v[54:57]
	v_mfma_f32_16x16x32_bf16 v[50:53], v[154:157], v[162:165], v[50:53]
	v_mfma_f32_16x16x32_bf16 v[50:53], v[158:161], v[166:169], v[50:53]
	v_mfma_f32_16x16x32_bf16 v[46:49], v[130:133], v[170:173], v[46:49]
	v_mfma_f32_16x16x32_bf16 v[46:49], v[134:137], v[174:177], v[46:49]
	v_mfma_f32_16x16x32_bf16 v[42:45], v[138:141], v[170:173], v[42:45]
	v_mfma_f32_16x16x32_bf16 v[42:45], v[142:145], v[174:177], v[42:45]
	v_mfma_f32_16x16x32_bf16 v[38:41], v[146:149], v[170:173], v[38:41]
	v_mfma_f32_16x16x32_bf16 v[38:41], v[150:153], v[174:177], v[38:41]
	v_mfma_f32_16x16x32_bf16 v[34:37], v[154:157], v[170:173], v[34:37]
	v_mfma_f32_16x16x32_bf16 v[34:37], v[158:161], v[174:177], v[34:37]
	v_mfma_f32_16x16x32_bf16 v[30:33], v[130:133], v[178:181], v[30:33]
	v_mfma_f32_16x16x32_bf16 v[30:33], v[134:137], v[182:185], v[30:33]
	v_mfma_f32_16x16x32_bf16 v[26:29], v[138:141], v[178:181], v[26:29]
	v_mfma_f32_16x16x32_bf16 v[26:29], v[142:145], v[182:185], v[26:29]
	v_mfma_f32_16x16x32_bf16 v[22:25], v[146:149], v[178:181], v[22:25]
	v_mfma_f32_16x16x32_bf16 v[22:25], v[150:153], v[182:185], v[22:25]
	v_mfma_f32_16x16x32_bf16 v[18:21], v[154:157], v[178:181], v[18:21]
	v_mfma_f32_16x16x32_bf16 v[18:21], v[158:161], v[182:185], v[18:21]
	v_mfma_f32_16x16x32_bf16 v[14:17], v[130:133], v[220:223], v[14:17]
	v_mfma_f32_16x16x32_bf16 v[14:17], v[134:137], v[224:227], v[14:17]
	v_mfma_f32_16x16x32_bf16 v[10:13], v[138:141], v[220:223], v[10:13]
	v_mfma_f32_16x16x32_bf16 v[10:13], v[142:145], v[224:227], v[10:13]
	v_mfma_f32_16x16x32_bf16 v[6:9], v[146:149], v[220:223], v[6:9]
	v_mfma_f32_16x16x32_bf16 v[6:9], v[150:153], v[224:227], v[6:9]
	v_mfma_f32_16x16x32_bf16 v[2:5], v[154:157], v[220:223], v[2:5]
	v_mfma_f32_16x16x32_bf16 v[2:5], v[158:161], v[224:227], v[2:5]
	s_barrier
	s_setprio 0
	s_add_i32 s73, 0, 0x18000
	s_add_i32 s74, 0, 0x1c000
	v_add_u32_e32 v142, s73, v1
	v_add_u32_e32 v158, s74, v1
	ds_read_b128 v[130:133], v142
	ds_read_b128 v[134:137], v142 offset:1024
	ds_read_b128 v[138:141], v142 offset:2048
	ds_read_b128 v[142:145], v142 offset:3072
	ds_read_b128 v[146:149], v158
	ds_read_b128 v[150:153], v158 offset:1024
	ds_read_b128 v[154:157], v158 offset:2048
	ds_read_b128 v[158:161], v158 offset:3072
	s_add_u32 s42, s42, 0x100000
	s_addc_u32 s43, s43, 0
	s_mov_b32 m0, s57
	v_lshl_add_u64 v[232:233], s[42:43], 0, v[186:187]
	ds_read_b128 v[162:165], v238 offset:32768
	ds_read_b128 v[166:169], v238 offset:33792
	ds_read_b128 v[170:173], v238 offset:34816
	ds_read_b128 v[174:177], v238 offset:35840
	ds_read_b128 v[178:181], v238 offset:36864
	ds_read_b128 v[182:185], v238 offset:37888
	ds_read_b128 v[220:223], v238 offset:38912
	ds_read_b128 v[224:227], v238 offset:39936
	global_load_lds_dwordx4 v[232:233], off
	v_lshl_add_u64 v[232:233], s[42:43], 0, v[190:191]
	s_mov_b32 m0, s58
	s_nop 0
	global_load_lds_dwordx4 v[232:233], off
	s_waitcnt vmcnt(8)
	s_waitcnt lgkmcnt(0)
	s_setprio 1
	s_barrier
	v_mfma_f32_16x16x32_bf16 v[90:93], v[130:133], v[162:165], v[90:93]
	v_mfma_f32_16x16x32_bf16 v[90:93], v[134:137], v[166:169], v[90:93]
	v_mfma_f32_16x16x32_bf16 v[98:101], v[138:141], v[162:165], v[98:101]
	v_mfma_f32_16x16x32_bf16 v[98:101], v[142:145], v[166:169], v[98:101]
	v_mfma_f32_16x16x32_bf16 v[106:109], v[146:149], v[162:165], v[106:109]
	v_mfma_f32_16x16x32_bf16 v[106:109], v[150:153], v[166:169], v[106:109]
	v_mfma_f32_16x16x32_bf16 v[114:117], v[154:157], v[162:165], v[114:117]
	v_mfma_f32_16x16x32_bf16 v[114:117], v[158:161], v[166:169], v[114:117]
	v_mfma_f32_16x16x32_bf16 v[122:125], v[130:133], v[170:173], v[122:125]
	v_mfma_f32_16x16x32_bf16 v[122:125], v[134:137], v[174:177], v[122:125]
	v_mfma_f32_16x16x32_bf16 v[126:129], v[138:141], v[170:173], v[126:129]
	v_mfma_f32_16x16x32_bf16 v[126:129], v[142:145], v[174:177], v[126:129]
	v_mfma_f32_16x16x32_bf16 v[118:121], v[146:149], v[170:173], v[118:121]
	v_mfma_f32_16x16x32_bf16 v[118:121], v[150:153], v[174:177], v[118:121]
	v_mfma_f32_16x16x32_bf16 v[110:113], v[154:157], v[170:173], v[110:113]
	v_mfma_f32_16x16x32_bf16 v[110:113], v[158:161], v[174:177], v[110:113]
	v_mfma_f32_16x16x32_bf16 v[102:105], v[130:133], v[178:181], v[102:105]
	v_mfma_f32_16x16x32_bf16 v[102:105], v[134:137], v[182:185], v[102:105]
	v_mfma_f32_16x16x32_bf16 v[94:97], v[138:141], v[178:181], v[94:97]
	v_mfma_f32_16x16x32_bf16 v[94:97], v[142:145], v[182:185], v[94:97]
	v_mfma_f32_16x16x32_bf16 v[86:89], v[146:149], v[178:181], v[86:89]
	v_mfma_f32_16x16x32_bf16 v[86:89], v[150:153], v[182:185], v[86:89]
	v_mfma_f32_16x16x32_bf16 v[82:85], v[154:157], v[178:181], v[82:85]
	v_mfma_f32_16x16x32_bf16 v[82:85], v[158:161], v[182:185], v[82:85]
	v_mfma_f32_16x16x32_bf16 v[78:81], v[130:133], v[220:223], v[78:81]
	v_mfma_f32_16x16x32_bf16 v[78:81], v[134:137], v[224:227], v[78:81]
	v_mfma_f32_16x16x32_bf16 v[74:77], v[138:141], v[220:223], v[74:77]
	v_mfma_f32_16x16x32_bf16 v[74:77], v[142:145], v[224:227], v[74:77]
	v_mfma_f32_16x16x32_bf16 v[70:73], v[146:149], v[220:223], v[70:73]
	v_mfma_f32_16x16x32_bf16 v[70:73], v[150:153], v[224:227], v[70:73]
	v_mfma_f32_16x16x32_bf16 v[66:69], v[154:157], v[220:223], v[66:69]
	v_mfma_f32_16x16x32_bf16 v[66:69], v[158:161], v[224:227], v[66:69]
	s_barrier
; #define PG8_STAGE(bufoff, gbase, voff) do { _Pragma("unroll") for (int _i = 0; _i < 2; ++_i) \
;         __builtin_amdgcn_global_load_lds((const unsigned*)((const char*)(gbase) + (voff)[_i]), (PG8_LAS unsigned*)(lds + (bufoff) + ldsw + _i * 8192), 16, 0, 0); } while (0)
; #define PG8_LDA(dst, b, h) do { _Pragma("unroll") for (int m = 0; m < 4; ++m) _Pragma("unroll") for (int k = 0; k < 2; ++k) dst[m][k] = *(const PG8_LAS bf16x8*)(lds + PG8_SA(b, h) + aoff + m * 2048 + k * 1024); } while (0)
; #define PG8_MMA(ai, bj, At, Bt) do { __builtin_amdgcn_s_setprio(1); _Pragma("unroll") for (int m = 0; m < 4; ++m) _Pragma("unroll") for (int n = 0; n < 2; ++n) _Pragma("unroll") for (int k = 0; k < 2; ++k) \
;         acc[ai][bj][m][n] = __builtin_amdgcn_mfma_f32_16x16x32_bf16(Bt[n][k], At[m][k], acc[ai][bj][m][n], 0, 0, 0); __builtin_amdgcn_s_setprio(0); } while (0)
; #define PG8_WAIT_V(n) asm volatile("s_waitcnt vmcnt(" #n ")" ::: "memory")
; #define PG8_WAIT_L(n) asm volatile("s_waitcnt lgkmcnt(" #n ")" ::: "memory")
; #define PG8_BAR __builtin_amdgcn_s_barrier()
; #define PG8_SCHED __builtin_amdgcn_sched_barrier(0)
; template <class Epi, class Sched, bool ALIGN_EPI = false, bool SP2 = false, bool A_TILED = false>
; __device__ __forceinline__ void gemm_phase(PG8_LAS unsigned char* lds, const Gemm g, const Sched& S, const Epi& E) {
;     ...
;             PG8_WAIT_V(8); PG8_WAIT_L(0); PG8_BAR; PG8_MMA(0, 0, At, B0); PG8_MMA(0, 1, At, B1); PG8_BAR; PG8_SCHED;
;             PG8_LDA(At, 1, 1); PG8_STAGE(PG8_SB(1, 0), b3, voffB); PG8_STAGE(PG8_SB(1, 1), b3 + hstepB, voffB); PG8_STAGE(PG8_SA(1, 0), a3, voffA);
;             PG8_WAIT_V(8); PG8_WAIT_L(0); PG8_BAR; PG8_MMA(1, 0, At, B0); PG8_MMA(1, 1, At, B1); PG8_BAR; PG8_SCHED;
;     ...
;         if constexpr (ALIGN_EPI) { if (wr == 0) PG8_BAR; }
	s_setprio 0
	s_add_u32 s42, s40, 0x8000
	s_addc_u32 s43, s41, 0
	s_add_i32 s73, s73, s54
	v_lshl_add_u64 v[232:233], s[42:43], 0, v[188:189]
	s_mov_b32 m0, s73
	ds_read_b128 v[162:165], v238 offset:49152
	ds_read_b128 v[166:169], v238 offset:50176
	ds_read_b128 v[170:173], v238 offset:51200
	ds_read_b128 v[174:177], v238 offset:52224
	ds_read_b128 v[178:181], v238 offset:53248
	ds_read_b128 v[182:185], v238 offset:54272
	ds_read_b128 v[220:223], v238 offset:55296
	ds_read_b128 v[224:227], v238 offset:56320
	global_load_lds_dwordx4 v[232:233], off
	s_add_i32 m0, s73, 0x2000
	s_add_u32 s40, s40, 0xc000
	v_lshl_add_u64 v[232:233], s[42:43], 0, v[192:193]
	s_addc_u32 s41, s41, 0
	s_add_i32 s42, s74, s54
	global_load_lds_dwordx4 v[232:233], off
	v_lshl_add_u64 v[232:233], s[40:41], 0, v[188:189]
	s_mov_b32 m0, s42
	v_lshl_add_u64 v[228:229], v[228:229], 0, s[12:13]
	global_load_lds_dwordx4 v[232:233], off
	v_lshl_add_u64 v[232:233], s[40:41], 0, v[192:193]
	s_add_i32 m0, s42, 0x2000
	s_nop 0
	global_load_lds_dwordx4 v[232:233], off
	s_mov_b32 m0, s61
	s_nop 0
	global_load_lds_dwordx4 v[228:229], off
	v_lshl_add_u64 v[228:229], v[230:231], 0, s[12:13]
	s_mov_b32 m0, s62
	s_nop 0
	global_load_lds_dwordx4 v[228:229], off
	s_waitcnt vmcnt(8)
	s_waitcnt lgkmcnt(0)
	s_setprio 1
	s_barrier
	v_mfma_f32_16x16x32_bf16 v[62:65], v[130:133], v[162:165], v[62:65]
	v_mfma_f32_16x16x32_bf16 v[62:65], v[134:137], v[166:169], v[62:65]
	v_mfma_f32_16x16x32_bf16 v[58:61], v[138:141], v[162:165], v[58:61]
	v_mfma_f32_16x16x32_bf16 v[58:61], v[142:145], v[166:169], v[58:61]
	v_mfma_f32_16x16x32_bf16 v[54:57], v[146:149], v[162:165], v[54:57]
	v_mfma_f32_16x16x32_bf16 v[54:57], v[150:153], v[166:169], v[54:57]
	v_mfma_f32_16x16x32_bf16 v[50:53], v[154:157], v[162:165], v[50:53]
	v_mfma_f32_16x16x32_bf16 v[50:53], v[158:161], v[166:169], v[50:53]
	v_mfma_f32_16x16x32_bf16 v[46:49], v[130:133], v[170:173], v[46:49]
	v_mfma_f32_16x16x32_bf16 v[46:49], v[134:137], v[174:177], v[46:49]
	v_mfma_f32_16x16x32_bf16 v[42:45], v[138:141], v[170:173], v[42:45]
	v_mfma_f32_16x16x32_bf16 v[42:45], v[142:145], v[174:177], v[42:45]
	v_mfma_f32_16x16x32_bf16 v[38:41], v[146:149], v[170:173], v[38:41]
	v_mfma_f32_16x16x32_bf16 v[38:41], v[150:153], v[174:177], v[38:41]
	v_mfma_f32_16x16x32_bf16 v[34:37], v[154:157], v[170:173], v[34:37]
	v_mfma_f32_16x16x32_bf16 v[34:37], v[158:161], v[174:177], v[34:37]
	v_mfma_f32_16x16x32_bf16 v[30:33], v[130:133], v[178:181], v[30:33]
	v_mfma_f32_16x16x32_bf16 v[30:33], v[134:137], v[182:185], v[30:33]
	v_mfma_f32_16x16x32_bf16 v[26:29], v[138:141], v[178:181], v[26:29]
	v_mfma_f32_16x16x32_bf16 v[26:29], v[142:145], v[182:185], v[26:29]
	v_mfma_f32_16x16x32_bf16 v[22:25], v[146:149], v[178:181], v[22:25]
	v_mfma_f32_16x16x32_bf16 v[22:25], v[150:153], v[182:185], v[22:25]
	v_mfma_f32_16x16x32_bf16 v[18:21], v[154:157], v[178:181], v[18:21]
	v_mfma_f32_16x16x32_bf16 v[18:21], v[158:161], v[182:185], v[18:21]
	v_mfma_f32_16x16x32_bf16 v[14:17], v[130:133], v[220:223], v[14:17]
	v_mfma_f32_16x16x32_bf16 v[14:17], v[134:137], v[224:227], v[14:17]
	v_mfma_f32_16x16x32_bf16 v[10:13], v[138:141], v[220:223], v[10:13]
	v_mfma_f32_16x16x32_bf16 v[10:13], v[142:145], v[224:227], v[10:13]
	v_mfma_f32_16x16x32_bf16 v[6:9], v[146:149], v[220:223], v[6:9]
	v_mfma_f32_16x16x32_bf16 v[6:9], v[150:153], v[224:227], v[6:9]
	v_mfma_f32_16x16x32_bf16 v[2:5], v[154:157], v[220:223], v[2:5]
	v_mfma_f32_16x16x32_bf16 v[2:5], v[158:161], v[224:227], v[2:5]
	s_barrier
	s_setprio 0
	s_add_i32 s72, s72, 2
	s_add_u32 s70, s70, 0x10000
	s_addc_u32 s71, s71, 0
	s_add_u32 s38, s38, 0x100
	s_addc_u32 s39, s39, 0
	s_cmp_gt_u32 s72, 61
	s_cbranch_scc0 .LBB0_1103
	s_and_b64 vcc, exec, s[14:15]
	s_cbranch_vccz .LBB0_1106
	s_barrier

; #define PG8_STAGE(bufoff, gbase, voff) do { _Pragma("unroll") for (int _i = 0; _i < 2; ++_i) \
;         __builtin_amdgcn_global_load_lds((const unsigned*)((const char*)(gbase) + (voff)[_i]), (PG8_LAS unsigned*)(lds + (bufoff) + ldsw + _i * 8192), 16, 0, 0); } while (0)
; #define PG8_LDA(dst, b, h) do { _Pragma("unroll") for (int m = 0; m < 4; ++m) _Pragma("unroll") for (int k = 0; k < 2; ++k) dst[m][k] = *(const PG8_LAS bf16x8*)(lds + PG8_SA(b, h) + aoff + m * 2048 + k * 1024); } while (0)
; #define PG8_LDB(dst, b, h) do { _Pragma("unroll") for (int n = 0; n < 2; ++n) _Pragma("unroll") for (int k = 0; k < 2; ++k) dst[n][k] = *(const PG8_LAS bf16x8*)(lds + PG8_SB(b, h) + boff + n * 2048 + k * 1024); } while (0)
; #define PG8_WAIT_V(n) asm volatile("s_waitcnt vmcnt(" #n ")" ::: "memory")
; #define PG8_BAR __builtin_amdgcn_s_barrier()
; template <class Epi, class Sched, bool ALIGN_EPI = false, bool SP2 = false, bool A_TILED = false>
; __device__ __forceinline__ void gemm_phase(PG8_LAS unsigned char* lds, const Gemm g, const Sched& S, const Epi& E) {
;     ...
;         const bool has_next = S.next(ui + 1, nxt);
;         const char* nA = has_next ? (const char*)g.A + (size_t)nxt.pm * tstepA : cA; const char* nB = has_next ? (const char*)g.Bt + (size_t)nxt.pn * tstepB : cB;
;         for (int t = 0; t < nt; t += 2) {
;             const bool last = (t == nt - 2);
;             const char* a1 = cA + (size_t)(t + 1) * kstepA;
;             const char* a2 = last ? nA : cA + (size_t)(t + 2) * kstepA; const char* b2 = last ? nB : cB + (size_t)(t + 2) * kstepB;
;             const char* a3 = a2 + kstepA; const char* b3 = b2 + kstepB;
;             if (last && has_next) S.a_ready(nxt);
;             if constexpr (SP2) {
;             PG8_LDB(B0, 0, 0); PG8_LDB(B1, 0, 1); PG8_SCHED; PG8_LDA(At, 0, 0); PG8_STAGE(PG8_SA(1, 1), a1 + hstepA, voffA);
;             PG8_WAIT_V(8); PG8_WAIT_L(0); PG8_BAR; PG8_MMA(0, 0, At, B0); PG8_MMA(0, 1, At, B1); PG8_BAR; PG8_SCHED;
;             PG8_LDA(At, 0, 1); PG8_STAGE(PG8_SB(0, 0), b2, voffB); PG8_STAGE(PG8_SB(0, 1), b2 + hstepB, voffB); PG8_STAGE(PG8_SA(0, 0), a2, voffA);
;             PG8_WAIT_V(8); PG8_WAIT_L(0); PG8_BAR; PG8_MMA(1, 0, At, B0); PG8_MMA(1, 1, At, B1); PG8_BAR; PG8_SCHED;
;             PG8_LDB(B0, 1, 0); PG8_LDB(B1, 1, 1); PG8_SCHED; PG8_LDA(At, 1, 0); PG8_STAGE(PG8_SA(0, 1), a2 + hstepA, voffA);
.LBB0_1171:
	s_ashr_i32 s17, s16, 31
	s_lshl_b64 s[18:19], s[16:17], 21
	s_add_u32 s18, s3, s18
	s_addc_u32 s19, s30, s19
	s_and_b64 s[20:21], s[0:1], exec
	s_cselect_b32 s17, s19, s23
	s_cselect_b32 s33, s18, s22
	s_ashr_i32 s15, s14, 31
	s_lshl_b64 s[20:21], s[14:15], 21
	s_add_u32 s20, s31, s20
	s_addc_u32 s21, s34, s21
	s_and_b64 s[26:27], s[0:1], exec
	s_cselect_b32 s15, s21, s25
	s_cselect_b32 s58, s20, s24
	s_add_u32 s22, s22, 0xc000
	s_addc_u32 s23, s23, 0
	s_add_u32 s59, s24, 0x10000
	v_mov_b32_e32 v2, 0
	s_addc_u32 s60, s25, 0
	s_mov_b32 s61, -2
	ds_read_b128 v[152:155], v141
	ds_read_b128 v[160:163], v141 offset:1024
	ds_read_b128 v[164:167], v141 offset:2048
	ds_read_b128 v[168:171], v141 offset:3072
	ds_read_b128 v[172:175], v156
	ds_read_b128 v[176:179], v156 offset:1024
	ds_read_b128 v[180:183], v156 offset:2048
	ds_read_b128 v[184:187], v156 offset:3072
	s_add_u32 s24, s22, 0x4000
	s_addc_u32 s25, s23, 0
	s_cmp_eq_u32 s61, 60
	s_cselect_b32 s28, s33, s24
	s_cselect_b32 s29, s17, s25
	s_cselect_b32 s26, s58, s59
	s_cselect_b32 s27, s15, s60
	s_add_u32 s24, s28, 0x8000
	s_addc_u32 s25, s29, 0
	s_add_i32 m0, s38, 0xc000
	ds_read_b128 v[188:191], v157
	ds_read_b128 v[192:195], v157 offset:1024
	ds_read_b128 v[196:199], v157 offset:2048
	ds_read_b128 v[200:203], v157 offset:3072
	ds_read_b128 v[204:207], v157 offset:4096
	ds_read_b128 v[208:211], v157 offset:5120
	ds_read_b128 v[212:215], v157 offset:6144
	ds_read_b128 v[216:219], v157 offset:7168
	global_load_lds_dwordx4 v144, s[22:23]
	s_add_i32 m0, s38, 0xe000
	s_nop 0
	global_load_lds_dwordx4 v146, s[22:23]
	s_waitcnt vmcnt(8)
	s_waitcnt lgkmcnt(0)
	s_setprio 1
	s_barrier
	v_mfma_f32_16x16x32_bf16 v[126:129], v[152:155], v[188:191], 0
	v_mfma_f32_16x16x32_bf16 v[126:129], v[160:163], v[192:195], v[126:129]
	v_mfma_f32_16x16x32_bf16 v[122:125], v[164:167], v[188:191], 0
	v_mfma_f32_16x16x32_bf16 v[122:125], v[168:171], v[192:195], v[122:125]
	v_mfma_f32_16x16x32_bf16 v[110:113], v[152:155], v[196:199], 0
	v_mfma_f32_16x16x32_bf16 v[110:113], v[160:163], v[200:203], v[110:113]
	v_mfma_f32_16x16x32_bf16 v[106:109], v[164:167], v[196:199], 0
	v_mfma_f32_16x16x32_bf16 v[106:109], v[168:171], v[200:203], v[106:109]
	v_mfma_f32_16x16x32_bf16 v[94:97], v[152:155], v[204:207], 0
	v_mfma_f32_16x16x32_bf16 v[94:97], v[160:163], v[208:211], v[94:97]
	v_mfma_f32_16x16x32_bf16 v[90:93], v[164:167], v[204:207], 0
	v_mfma_f32_16x16x32_bf16 v[90:93], v[168:171], v[208:211], v[90:93]
	v_mfma_f32_16x16x32_bf16 v[78:81], v[152:155], v[212:215], 0
	v_mfma_f32_16x16x32_bf16 v[78:81], v[160:163], v[216:219], v[78:81]
	v_mfma_f32_16x16x32_bf16 v[74:77], v[164:167], v[212:215], 0
	v_mfma_f32_16x16x32_bf16 v[74:77], v[168:171], v[216:219], v[74:77]
	v_mfma_f32_16x16x32_bf16 v[118:121], v[172:175], v[188:191], 0
	v_mfma_f32_16x16x32_bf16 v[118:121], v[176:179], v[192:195], v[118:121]
	v_mfma_f32_16x16x32_bf16 v[114:117], v[180:183], v[188:191], 0
	v_mfma_f32_16x16x32_bf16 v[114:117], v[184:187], v[192:195], v[114:117]
	v_mfma_f32_16x16x32_bf16 v[102:105], v[172:175], v[196:199], 0
	v_mfma_f32_16x16x32_bf16 v[102:105], v[176:179], v[200:203], v[102:105]
	v_mfma_f32_16x16x32_bf16 v[98:101], v[180:183], v[196:199], 0
	v_mfma_f32_16x16x32_bf16 v[98:101], v[184:187], v[200:203], v[98:101]
	v_mfma_f32_16x16x32_bf16 v[86:89], v[172:175], v[204:207], 0
	v_mfma_f32_16x16x32_bf16 v[86:89], v[176:179], v[208:211], v[86:89]
	v_mfma_f32_16x16x32_bf16 v[82:85], v[180:183], v[204:207], 0
	v_mfma_f32_16x16x32_bf16 v[82:85], v[184:187], v[208:211], v[82:85]
	v_mfma_f32_16x16x32_bf16 v[70:73], v[172:175], v[212:215], 0
	v_mfma_f32_16x16x32_bf16 v[70:73], v[176:179], v[216:219], v[70:73]
	v_mfma_f32_16x16x32_bf16 v[66:69], v[180:183], v[212:215], 0
	v_mfma_f32_16x16x32_bf16 v[66:69], v[184:187], v[216:219], v[66:69]
	s_barrier
	s_setprio 0
	s_add_i32 s62, s55, s35
	s_mov_b32 m0, s62
	ds_read_b128 v[188:191], v157 offset:16384
	ds_read_b128 v[192:195], v157 offset:17408
	ds_read_b128 v[196:199], v157 offset:18432
	ds_read_b128 v[200:203], v157 offset:19456
	ds_read_b128 v[204:207], v157 offset:20480
	ds_read_b128 v[208:211], v157 offset:21504
	ds_read_b128 v[212:215], v157 offset:22528
	ds_read_b128 v[216:219], v157 offset:23552
	global_load_lds_dwordx4 v132, s[26:27]
	s_add_i32 m0, s62, 0x2000
	s_add_u32 s62, s26, 0x4000
	s_addc_u32 s63, s27, 0
	s_add_i32 s64, s56, s35
	global_load_lds_dwordx4 v136, s[26:27]
	s_mov_b32 m0, s64
	s_nop 0
	global_load_lds_dwordx4 v132, s[62:63]
	s_add_i32 m0, s64, 0x2000
	s_nop 0
	global_load_lds_dwordx4 v136, s[62:63]
	s_mov_b32 m0, s38
	s_nop 0
	global_load_lds_dwordx4 v130, s[28:29]
	s_mov_b32 m0, s39
	s_nop 0
	global_load_lds_dwordx4 v134, s[28:29]
	s_waitcnt vmcnt(8)
	s_waitcnt lgkmcnt(0)
	s_setprio 1
	s_barrier
; #define PG8_STAGE(bufoff, gbase, voff) do { _Pragma("unroll") for (int _i = 0; _i < 2; ++_i) \
;         __builtin_amdgcn_global_load_lds((const unsigned*)((const char*)(gbase) + (voff)[_i]), (PG8_LAS unsigned*)(lds + (bufoff) + ldsw + _i * 8192), 16, 0, 0); } while (0)
; #define PG8_LDA(dst, b, h) do { _Pragma("unroll") for (int m = 0; m < 4; ++m) _Pragma("unroll") for (int k = 0; k < 2; ++k) dst[m][k] = *(const PG8_LAS bf16x8*)(lds + PG8_SA(b, h) + aoff + m * 2048 + k * 1024); } while (0)
; #define PG8_LDB(dst, b, h) do { _Pragma("unroll") for (int n = 0; n < 2; ++n) _Pragma("unroll") for (int k = 0; k < 2; ++k) dst[n][k] = *(const PG8_LAS bf16x8*)(lds + PG8_SB(b, h) + boff + n * 2048 + k * 1024); } while (0)
; #define PG8_MMA(ai, bj, At, Bt) do { __builtin_amdgcn_s_setprio(1); _Pragma("unroll") for (int m = 0; m < 4; ++m) _Pragma("unroll") for (int n = 0; n < 2; ++n) _Pragma("unroll") for (int k = 0; k < 2; ++k) \
;         acc[ai][bj][m][n] = __builtin_amdgcn_mfma_f32_16x16x32_bf16(Bt[n][k], At[m][k], acc[ai][bj][m][n], 0, 0, 0); __builtin_amdgcn_s_setprio(0); } while (0)
; #define PG8_WAIT_V(n) asm volatile("s_waitcnt vmcnt(" #n ")" ::: "memory")
; #define PG8_WAIT_L(n) asm volatile("s_waitcnt lgkmcnt(" #n ")" ::: "memory")
; #define PG8_BAR __builtin_amdgcn_s_barrier()
; #define PG8_SCHED __builtin_amdgcn_sched_barrier(0)
; template <class Epi, class Sched, bool ALIGN_EPI = false, bool SP2 = false, bool A_TILED = false>
; __device__ __forceinline__ void gemm_phase(PG8_LAS unsigned char* lds, const Gemm g, const Sched& S, const Epi& E) {
;     ...
;             PG8_WAIT_V(8); PG8_WAIT_L(0); PG8_BAR; PG8_MMA(1, 0, At, B0); PG8_MMA(1, 1, At, B1); PG8_BAR; PG8_SCHED;
;             PG8_LDB(B0, 1, 0); PG8_LDB(B1, 1, 1); PG8_SCHED; PG8_LDA(At, 1, 0); PG8_STAGE(PG8_SA(0, 1), a2 + hstepA, voffA);
;             PG8_WAIT_V(8); PG8_WAIT_L(0); PG8_BAR; PG8_MMA(0, 0, At, B0); PG8_MMA(0, 1, At, B1); PG8_BAR; PG8_SCHED;
;             PG8_LDA(At, 1, 1); PG8_STAGE(PG8_SB(1, 0), b3, voffB); PG8_STAGE(PG8_SB(1, 1), b3 + hstepB, voffB); PG8_STAGE(PG8_SA(1, 0), a3, voffA);
	v_mfma_f32_16x16x32_bf16 v[62:65], v[152:155], v[188:191], 0
	v_mfma_f32_16x16x32_bf16 v[62:65], v[160:163], v[192:195], v[62:65]
	v_mfma_f32_16x16x32_bf16 v[58:61], v[164:167], v[188:191], 0
	v_mfma_f32_16x16x32_bf16 v[58:61], v[168:171], v[192:195], v[58:61]
	v_mfma_f32_16x16x32_bf16 v[54:57], v[172:175], v[188:191], 0
	v_mfma_f32_16x16x32_bf16 v[54:57], v[176:179], v[192:195], v[54:57]
	v_mfma_f32_16x16x32_bf16 v[50:53], v[180:183], v[188:191], 0
	v_mfma_f32_16x16x32_bf16 v[50:53], v[184:187], v[192:195], v[50:53]
	v_mfma_f32_16x16x32_bf16 v[46:49], v[152:155], v[196:199], 0
	v_mfma_f32_16x16x32_bf16 v[46:49], v[160:163], v[200:203], v[46:49]
	v_mfma_f32_16x16x32_bf16 v[42:45], v[164:167], v[196:199], 0
	v_mfma_f32_16x16x32_bf16 v[42:45], v[168:171], v[200:203], v[42:45]
	v_mfma_f32_16x16x32_bf16 v[38:41], v[172:175], v[196:199], 0
	v_mfma_f32_16x16x32_bf16 v[38:41], v[176:179], v[200:203], v[38:41]
	v_mfma_f32_16x16x32_bf16 v[34:37], v[180:183], v[196:199], 0
	v_mfma_f32_16x16x32_bf16 v[34:37], v[184:187], v[200:203], v[34:37]
	v_mfma_f32_16x16x32_bf16 v[30:33], v[152:155], v[204:207], 0
	v_mfma_f32_16x16x32_bf16 v[30:33], v[160:163], v[208:211], v[30:33]
	v_mfma_f32_16x16x32_bf16 v[26:29], v[164:167], v[204:207], 0
	v_mfma_f32_16x16x32_bf16 v[26:29], v[168:171], v[208:211], v[26:29]
	v_mfma_f32_16x16x32_bf16 v[22:25], v[172:175], v[204:207], 0
	v_mfma_f32_16x16x32_bf16 v[22:25], v[176:179], v[208:211], v[22:25]
	v_mfma_f32_16x16x32_bf16 v[18:21], v[180:183], v[204:207], 0
	v_mfma_f32_16x16x32_bf16 v[18:21], v[184:187], v[208:211], v[18:21]
	v_mfma_f32_16x16x32_bf16 v[14:17], v[152:155], v[212:215], 0
	v_mfma_f32_16x16x32_bf16 v[14:17], v[160:163], v[216:219], v[14:17]
	v_mfma_f32_16x16x32_bf16 v[10:13], v[164:167], v[212:215], 0
	v_mfma_f32_16x16x32_bf16 v[10:13], v[168:171], v[216:219], v[10:13]
	v_mfma_f32_16x16x32_bf16 v[6:9], v[172:175], v[212:215], 0
	v_mfma_f32_16x16x32_bf16 v[6:9], v[176:179], v[216:219], v[6:9]
	v_mfma_f32_16x16x32_bf16 v[2:5], v[180:183], v[212:215], 0
	v_mfma_f32_16x16x32_bf16 v[2:5], v[184:187], v[216:219], v[2:5]
	s_barrier
	s_setprio 0
	s_add_i32 s62, 0, 0x18000
	s_add_i32 s63, 0, 0x1c000
	ds_read_b128 v[152:155], v141 offset:32768
	ds_read_b128 v[160:163], v141 offset:33792
	ds_read_b128 v[164:167], v141 offset:34816
	ds_read_b128 v[168:171], v141 offset:35840
	ds_read_b128 v[172:175], v141 offset:49152
	ds_read_b128 v[176:179], v141 offset:50176
	ds_read_b128 v[180:183], v141 offset:51200
	ds_read_b128 v[184:187], v141 offset:52224
	s_add_u32 s28, s28, 0x4000
	s_addc_u32 s29, s29, 0
	s_mov_b32 m0, s40
	ds_read_b128 v[188:191], v157 offset:32768
	ds_read_b128 v[192:195], v157 offset:33792
	ds_read_b128 v[196:199], v157 offset:34816
	ds_read_b128 v[200:203], v157 offset:35840
	ds_read_b128 v[204:207], v157 offset:36864
	ds_read_b128 v[208:211], v157 offset:37888
	ds_read_b128 v[212:215], v157 offset:38912
	ds_read_b128 v[216:219], v157 offset:39936
	global_load_lds_dwordx4 v130, s[28:29]
	s_mov_b32 m0, s41
	s_nop 0
	global_load_lds_dwordx4 v134, s[28:29]
	s_waitcnt vmcnt(8)
	s_waitcnt lgkmcnt(0)
	s_setprio 1
	s_barrier
	v_mfma_f32_16x16x32_bf16 v[126:129], v[152:155], v[188:191], v[126:129]
	v_mfma_f32_16x16x32_bf16 v[126:129], v[160:163], v[192:195], v[126:129]
	v_mfma_f32_16x16x32_bf16 v[122:125], v[164:167], v[188:191], v[122:125]
	v_mfma_f32_16x16x32_bf16 v[122:125], v[168:171], v[192:195], v[122:125]
	v_mfma_f32_16x16x32_bf16 v[118:121], v[172:175], v[188:191], v[118:121]
	v_mfma_f32_16x16x32_bf16 v[118:121], v[176:179], v[192:195], v[118:121]
	v_mfma_f32_16x16x32_bf16 v[114:117], v[180:183], v[188:191], v[114:117]
	v_mfma_f32_16x16x32_bf16 v[114:117], v[184:187], v[192:195], v[114:117]
	v_mfma_f32_16x16x32_bf16 v[110:113], v[152:155], v[196:199], v[110:113]
	v_mfma_f32_16x16x32_bf16 v[110:113], v[160:163], v[200:203], v[110:113]
	v_mfma_f32_16x16x32_bf16 v[106:109], v[164:167], v[196:199], v[106:109]
	v_mfma_f32_16x16x32_bf16 v[106:109], v[168:171], v[200:203], v[106:109]
	v_mfma_f32_16x16x32_bf16 v[102:105], v[172:175], v[196:199], v[102:105]
	v_mfma_f32_16x16x32_bf16 v[102:105], v[176:179], v[200:203], v[102:105]
	v_mfma_f32_16x16x32_bf16 v[98:101], v[180:183], v[196:199], v[98:101]
	v_mfma_f32_16x16x32_bf16 v[98:101], v[184:187], v[200:203], v[98:101]
	v_mfma_f32_16x16x32_bf16 v[94:97], v[152:155], v[204:207], v[94:97]
	v_mfma_f32_16x16x32_bf16 v[94:97], v[160:163], v[208:211], v[94:97]
	v_mfma_f32_16x16x32_bf16 v[90:93], v[164:167], v[204:207], v[90:93]
	v_mfma_f32_16x16x32_bf16 v[90:93], v[168:171], v[208:211], v[90:93]
	v_mfma_f32_16x16x32_bf16 v[86:89], v[172:175], v[204:207], v[86:89]
	v_mfma_f32_16x16x32_bf16 v[86:89], v[176:179], v[208:211], v[86:89]
	v_mfma_f32_16x16x32_bf16 v[82:85], v[180:183], v[204:207], v[82:85]
	v_mfma_f32_16x16x32_bf16 v[82:85], v[184:187], v[208:211], v[82:85]
	v_mfma_f32_16x16x32_bf16 v[78:81], v[152:155], v[212:215], v[78:81]
	v_mfma_f32_16x16x32_bf16 v[78:81], v[160:163], v[216:219], v[78:81]
	v_mfma_f32_16x16x32_bf16 v[74:77], v[164:167], v[212:215], v[74:77]
	v_mfma_f32_16x16x32_bf16 v[74:77], v[168:171], v[216:219], v[74:77]
	v_mfma_f32_16x16x32_bf16 v[70:73], v[172:175], v[212:215], v[70:73]
	v_mfma_f32_16x16x32_bf16 v[70:73], v[176:179], v[216:219], v[70:73]
	v_mfma_f32_16x16x32_bf16 v[66:69], v[180:183], v[212:215], v[66:69]
	v_mfma_f32_16x16x32_bf16 v[66:69], v[184:187], v[216:219], v[66:69]
	s_barrier
; #define PG8_STAGE(bufoff, gbase, voff) do { _Pragma("unroll") for (int _i = 0; _i < 2; ++_i) \
;         __builtin_amdgcn_global_load_lds((const unsigned*)((const char*)(gbase) + (voff)[_i]), (PG8_LAS unsigned*)(lds + (bufoff) + ldsw + _i * 8192), 16, 0, 0); } while (0)
; #define PG8_LDA(dst, b, h) do { _Pragma("unroll") for (int m = 0; m < 4; ++m) _Pragma("unroll") for (int k = 0; k < 2; ++k) dst[m][k] = *(const PG8_LAS bf16x8*)(lds + PG8_SA(b, h) + aoff + m * 2048 + k * 1024); } while (0)
; #define PG8_LDB(dst, b, h) do { _Pragma("unroll") for (int n = 0; n < 2; ++n) _Pragma("unroll") for (int k = 0; k < 2; ++k) dst[n][k] = *(const PG8_LAS bf16x8*)(lds + PG8_SB(b, h) + boff + n * 2048 + k * 1024); } while (0)
; #define PG8_MMA(ai, bj, At, Bt) do { __builtin_amdgcn_s_setprio(1); _Pragma("unroll") for (int m = 0; m < 4; ++m) _Pragma("unroll") for (int n = 0; n < 2; ++n) _Pragma("unroll") for (int k = 0; k < 2; ++k) \
;         acc[ai][bj][m][n] = __builtin_amdgcn_mfma_f32_16x16x32_bf16(Bt[n][k], At[m][k], acc[ai][bj][m][n], 0, 0, 0); __builtin_amdgcn_s_setprio(0); } while (0)
; template <class Epi, class Sched, bool ALIGN_EPI = false, bool SP2 = false, bool A_TILED = false>
; __device__ __forceinline__ void gemm_phase(PG8_LAS unsigned char* lds, const Gemm g, const Sched& S, const Epi& E) {
;     ...
;         for (int t = 0; t < nt; t += 2) {
;             const bool last = (t == nt - 2);
;             const char* a1 = cA + (size_t)(t + 1) * kstepA;
;             const char* a2 = last ? nA : cA + (size_t)(t + 2) * kstepA; const char* b2 = last ? nB : cB + (size_t)(t + 2) * kstepB;
;             const char* a3 = a2 + kstepA; const char* b3 = b2 + kstepB;
;             if (last && has_next) S.a_ready(nxt);
;             if constexpr (SP2) {
;             PG8_LDB(B0, 0, 0); PG8_LDB(B1, 0, 1); PG8_SCHED; PG8_LDA(At, 0, 0); PG8_STAGE(PG8_SA(1, 1), a1 + hstepA, voffA);
;             PG8_WAIT_V(8); PG8_WAIT_L(0); PG8_BAR; PG8_MMA(0, 0, At, B0); PG8_MMA(0, 1, At, B1); PG8_BAR; PG8_SCHED;
;     ...
;             PG8_WAIT_V(8); PG8_WAIT_L(0); PG8_BAR; PG8_MMA(0, 0, At, B0); PG8_MMA(0, 1, At, B1); PG8_BAR; PG8_SCHED;
;             PG8_LDA(At, 1, 1); PG8_STAGE(PG8_SB(1, 0), b3, voffB); PG8_STAGE(PG8_SB(1, 1), b3 + hstepB, voffB); PG8_STAGE(PG8_SA(1, 0), a3, voffA);
;             PG8_WAIT_V(8); PG8_WAIT_L(0); PG8_BAR; PG8_MMA(1, 0, At, B0); PG8_MMA(1, 1, At, B1); PG8_BAR; PG8_SCHED;
	s_setprio 0
	s_add_u32 s28, s26, 0x8000
	s_addc_u32 s29, s27, 0
	s_add_i32 s62, s62, s35
	s_mov_b32 m0, s62
	ds_read_b128 v[188:191], v157 offset:49152
	ds_read_b128 v[192:195], v157 offset:50176
	ds_read_b128 v[196:199], v157 offset:51200
	ds_read_b128 v[200:203], v157 offset:52224
	ds_read_b128 v[204:207], v157 offset:53248
	ds_read_b128 v[208:211], v157 offset:54272
	ds_read_b128 v[212:215], v157 offset:55296
	ds_read_b128 v[216:219], v157 offset:56320
	global_load_lds_dwordx4 v132, s[28:29]
	s_add_i32 m0, s62, 0x2000
	s_add_u32 s26, s26, 0xc000
	v_lshl_add_u64 v[220:221], s[28:29], 0, v[136:137]
	s_addc_u32 s27, s27, 0
	s_add_i32 s28, s63, s35
	global_load_lds_dwordx4 v[220:221], off
	s_mov_b32 m0, s28
	s_nop 0
	global_load_lds_dwordx4 v132, s[26:27]
	s_add_i32 m0, s28, 0x2000
	s_nop 0
	global_load_lds_dwordx4 v136, s[26:27]
	s_mov_b32 m0, s45
	s_nop 0
	global_load_lds_dwordx4 v130, s[24:25]
	s_mov_b32 m0, s54
	s_nop 0
	global_load_lds_dwordx4 v134, s[24:25]
	s_waitcnt vmcnt(8)
	s_waitcnt lgkmcnt(0)
	s_setprio 1
	s_barrier
	v_mfma_f32_16x16x32_bf16 v[62:65], v[152:155], v[188:191], v[62:65]
	v_mfma_f32_16x16x32_bf16 v[62:65], v[160:163], v[192:195], v[62:65]
	v_mfma_f32_16x16x32_bf16 v[58:61], v[164:167], v[188:191], v[58:61]
	v_mfma_f32_16x16x32_bf16 v[58:61], v[168:171], v[192:195], v[58:61]
	v_mfma_f32_16x16x32_bf16 v[54:57], v[172:175], v[188:191], v[54:57]
	v_mfma_f32_16x16x32_bf16 v[54:57], v[176:179], v[192:195], v[54:57]
	v_mfma_f32_16x16x32_bf16 v[50:53], v[180:183], v[188:191], v[50:53]
	v_mfma_f32_16x16x32_bf16 v[50:53], v[184:187], v[192:195], v[50:53]
	v_mfma_f32_16x16x32_bf16 v[46:49], v[152:155], v[196:199], v[46:49]
	v_mfma_f32_16x16x32_bf16 v[46:49], v[160:163], v[200:203], v[46:49]
	v_mfma_f32_16x16x32_bf16 v[42:45], v[164:167], v[196:199], v[42:45]
	v_mfma_f32_16x16x32_bf16 v[42:45], v[168:171], v[200:203], v[42:45]
	v_mfma_f32_16x16x32_bf16 v[38:41], v[172:175], v[196:199], v[38:41]
	v_mfma_f32_16x16x32_bf16 v[38:41], v[176:179], v[200:203], v[38:41]
	v_mfma_f32_16x16x32_bf16 v[34:37], v[180:183], v[196:199], v[34:37]
	v_mfma_f32_16x16x32_bf16 v[34:37], v[184:187], v[200:203], v[34:37]
	v_mfma_f32_16x16x32_bf16 v[30:33], v[152:155], v[204:207], v[30:33]
	v_mfma_f32_16x16x32_bf16 v[30:33], v[160:163], v[208:211], v[30:33]
	v_mfma_f32_16x16x32_bf16 v[26:29], v[164:167], v[204:207], v[26:29]
	v_mfma_f32_16x16x32_bf16 v[26:29], v[168:171], v[208:211], v[26:29]
	v_mfma_f32_16x16x32_bf16 v[22:25], v[172:175], v[204:207], v[22:25]
	v_mfma_f32_16x16x32_bf16 v[22:25], v[176:179], v[208:211], v[22:25]
	v_mfma_f32_16x16x32_bf16 v[18:21], v[180:183], v[204:207], v[18:21]
	v_mfma_f32_16x16x32_bf16 v[18:21], v[184:187], v[208:211], v[18:21]
	v_mfma_f32_16x16x32_bf16 v[14:17], v[152:155], v[212:215], v[14:17]
	v_mfma_f32_16x16x32_bf16 v[14:17], v[160:163], v[216:219], v[14:17]
	v_mfma_f32_16x16x32_bf16 v[10:13], v[164:167], v[212:215], v[10:13]
	v_mfma_f32_16x16x32_bf16 v[10:13], v[168:171], v[216:219], v[10:13]
	v_mfma_f32_16x16x32_bf16 v[6:9], v[172:175], v[212:215], v[6:9]
	v_mfma_f32_16x16x32_bf16 v[6:9], v[176:179], v[216:219], v[6:9]
	v_mfma_f32_16x16x32_bf16 v[2:5], v[180:183], v[212:215], v[2:5]
	v_mfma_f32_16x16x32_bf16 v[2:5], v[184:187], v[216:219], v[2:5]
	s_barrier
	s_setprio 0
	s_add_i32 s61, s61, 2
	s_add_u32 s22, s22, 0x10000
	s_addc_u32 s23, s23, 0
	s_add_u32 s59, s59, 0x10000
	s_addc_u32 s60, s60, 0
.LBB0_1172:
	ds_read_b128 v[152:155], v141
	ds_read_b128 v[160:163], v141 offset:1024
	ds_read_b128 v[164:167], v141 offset:2048
	ds_read_b128 v[168:171], v141 offset:3072
	ds_read_b128 v[172:175], v156
	ds_read_b128 v[176:179], v156 offset:1024
	ds_read_b128 v[180:183], v156 offset:2048
	ds_read_b128 v[184:187], v156 offset:3072
	s_add_u32 s24, s22, 0x4000
	s_addc_u32 s25, s23, 0
	s_cmp_eq_u32 s61, 60
	s_cselect_b32 s28, s33, s24
	s_cselect_b32 s29, s17, s25
	s_cselect_b32 s26, s58, s59
	s_cselect_b32 s27, s15, s60
	s_add_u32 s24, s28, 0x8000
	s_addc_u32 s25, s29, 0
	s_add_i32 m0, s38, 0xc000
	ds_read_b128 v[188:191], v157
	ds_read_b128 v[192:195], v157 offset:1024
	ds_read_b128 v[196:199], v157 offset:2048
	ds_read_b128 v[200:203], v157 offset:3072
	ds_read_b128 v[204:207], v157 offset:4096
	ds_read_b128 v[208:211], v157 offset:5120
	ds_read_b128 v[212:215], v157 offset:6144
	ds_read_b128 v[216:219], v157 offset:7168
	global_load_lds_dwordx4 v144, s[22:23]
	s_add_i32 m0, s38, 0xe000
	s_nop 0
	global_load_lds_dwordx4 v146, s[22:23]
	s_waitcnt vmcnt(8)
	s_waitcnt lgkmcnt(0)
	s_setprio 1
	s_barrier
; #define PG8_STAGE(bufoff, gbase, voff) do { _Pragma("unroll") for (int _i = 0; _i < 2; ++_i) \
;         __builtin_amdgcn_global_load_lds((const unsigned*)((const char*)(gbase) + (voff)[_i]), (PG8_LAS unsigned*)(lds + (bufoff) + ldsw + _i * 8192), 16, 0, 0); } while (0)
; #define PG8_LDA(dst, b, h) do { _Pragma("unroll") for (int m = 0; m < 4; ++m) _Pragma("unroll") for (int k = 0; k < 2; ++k) dst[m][k] = *(const PG8_LAS bf16x8*)(lds + PG8_SA(b, h) + aoff + m * 2048 + k * 1024); } while (0)
; #define PG8_LDB(dst, b, h) do { _Pragma("unroll") for (int n = 0; n < 2; ++n) _Pragma("unroll") for (int k = 0; k < 2; ++k) dst[n][k] = *(const PG8_LAS bf16x8*)(lds + PG8_SB(b, h) + boff + n * 2048 + k * 1024); } while (0)
; #define PG8_MMA(ai, bj, At, Bt) do { __builtin_amdgcn_s_setprio(1); _Pragma("unroll") for (int m = 0; m < 4; ++m) _Pragma("unroll") for (int n = 0; n < 2; ++n) _Pragma("unroll") for (int k = 0; k < 2; ++k) \
;         acc[ai][bj][m][n] = __builtin_amdgcn_mfma_f32_16x16x32_bf16(Bt[n][k], At[m][k], acc[ai][bj][m][n], 0, 0, 0); __builtin_amdgcn_s_setprio(0); } while (0)
; #define PG8_WAIT_V(n) asm volatile("s_waitcnt vmcnt(" #n ")" ::: "memory")
; #define PG8_WAIT_L(n) asm volatile("s_waitcnt lgkmcnt(" #n ")" ::: "memory")
; #define PG8_BAR __builtin_amdgcn_s_barrier()
; #define PG8_SCHED __builtin_amdgcn_sched_barrier(0)
; template <class Epi, class Sched, bool ALIGN_EPI = false, bool SP2 = false, bool A_TILED = false>
; __device__ __forceinline__ void gemm_phase(PG8_LAS unsigned char* lds, const Gemm g, const Sched& S, const Epi& E) {
;     ...
;             PG8_LDB(B0, 0, 0); PG8_LDB(B1, 0, 1); PG8_SCHED; PG8_LDA(At, 0, 0); PG8_STAGE(PG8_SA(1, 1), a1 + hstepA, voffA);
;             PG8_WAIT_V(8); PG8_WAIT_L(0); PG8_BAR; PG8_MMA(0, 0, At, B0); PG8_MMA(0, 1, At, B1); PG8_BAR; PG8_SCHED;
;             PG8_LDA(At, 0, 1); PG8_STAGE(PG8_SB(0, 0), b2, voffB); PG8_STAGE(PG8_SB(0, 1), b2 + hstepB, voffB); PG8_STAGE(PG8_SA(0, 0), a2, voffA);
;             PG8_WAIT_V(8); PG8_WAIT_L(0); PG8_BAR; PG8_MMA(1, 0, At, B0); PG8_MMA(1, 1, At, B1); PG8_BAR; PG8_SCHED;
;             PG8_LDB(B0, 1, 0); PG8_LDB(B1, 1, 1); PG8_SCHED; PG8_LDA(At, 1, 0); PG8_STAGE(PG8_SA(0, 1), a2 + hstepA, voffA);
;             PG8_WAIT_V(8); PG8_WAIT_L(0); PG8_BAR; PG8_MMA(0, 0, At, B0); PG8_MMA(0, 1, At, B1); PG8_BAR; PG8_SCHED;
	v_mfma_f32_16x16x32_bf16 v[126:129], v[152:155], v[188:191], v[126:129]
	v_mfma_f32_16x16x32_bf16 v[126:129], v[160:163], v[192:195], v[126:129]
	v_mfma_f32_16x16x32_bf16 v[122:125], v[164:167], v[188:191], v[122:125]
	v_mfma_f32_16x16x32_bf16 v[122:125], v[168:171], v[192:195], v[122:125]
	v_mfma_f32_16x16x32_bf16 v[110:113], v[152:155], v[196:199], v[110:113]
	v_mfma_f32_16x16x32_bf16 v[110:113], v[160:163], v[200:203], v[110:113]
	v_mfma_f32_16x16x32_bf16 v[106:109], v[164:167], v[196:199], v[106:109]
	v_mfma_f32_16x16x32_bf16 v[106:109], v[168:171], v[200:203], v[106:109]
	v_mfma_f32_16x16x32_bf16 v[94:97], v[152:155], v[204:207], v[94:97]
	v_mfma_f32_16x16x32_bf16 v[94:97], v[160:163], v[208:211], v[94:97]
	v_mfma_f32_16x16x32_bf16 v[90:93], v[164:167], v[204:207], v[90:93]
	v_mfma_f32_16x16x32_bf16 v[90:93], v[168:171], v[208:211], v[90:93]
	v_mfma_f32_16x16x32_bf16 v[78:81], v[152:155], v[212:215], v[78:81]
	v_mfma_f32_16x16x32_bf16 v[78:81], v[160:163], v[216:219], v[78:81]
	v_mfma_f32_16x16x32_bf16 v[74:77], v[164:167], v[212:215], v[74:77]
	v_mfma_f32_16x16x32_bf16 v[74:77], v[168:171], v[216:219], v[74:77]
	v_mfma_f32_16x16x32_bf16 v[118:121], v[172:175], v[188:191], v[118:121]
	v_mfma_f32_16x16x32_bf16 v[118:121], v[176:179], v[192:195], v[118:121]
	v_mfma_f32_16x16x32_bf16 v[114:117], v[180:183], v[188:191], v[114:117]
	v_mfma_f32_16x16x32_bf16 v[114:117], v[184:187], v[192:195], v[114:117]
	v_mfma_f32_16x16x32_bf16 v[102:105], v[172:175], v[196:199], v[102:105]
	v_mfma_f32_16x16x32_bf16 v[102:105], v[176:179], v[200:203], v[102:105]
	v_mfma_f32_16x16x32_bf16 v[98:101], v[180:183], v[196:199], v[98:101]
	v_mfma_f32_16x16x32_bf16 v[98:101], v[184:187], v[200:203], v[98:101]
	v_mfma_f32_16x16x32_bf16 v[86:89], v[172:175], v[204:207], v[86:89]
	v_mfma_f32_16x16x32_bf16 v[86:89], v[176:179], v[208:211], v[86:89]
	v_mfma_f32_16x16x32_bf16 v[82:85], v[180:183], v[204:207], v[82:85]
	v_mfma_f32_16x16x32_bf16 v[82:85], v[184:187], v[208:211], v[82:85]
	v_mfma_f32_16x16x32_bf16 v[70:73], v[172:175], v[212:215], v[70:73]
	v_mfma_f32_16x16x32_bf16 v[70:73], v[176:179], v[216:219], v[70:73]
	v_mfma_f32_16x16x32_bf16 v[66:69], v[180:183], v[212:215], v[66:69]
	v_mfma_f32_16x16x32_bf16 v[66:69], v[184:187], v[216:219], v[66:69]
	s_barrier
	s_setprio 0
	s_add_i32 s62, s55, s35
	s_mov_b32 m0, s62
	ds_read_b128 v[188:191], v157 offset:16384
	ds_read_b128 v[192:195], v157 offset:17408
	ds_read_b128 v[196:199], v157 offset:18432
	ds_read_b128 v[200:203], v157 offset:19456
	ds_read_b128 v[204:207], v157 offset:20480
	ds_read_b128 v[208:211], v157 offset:21504
	ds_read_b128 v[212:215], v157 offset:22528
	ds_read_b128 v[216:219], v157 offset:23552
	global_load_lds_dwordx4 v132, s[26:27]
	s_add_i32 m0, s62, 0x2000
	s_add_u32 s62, s26, 0x4000
	s_addc_u32 s63, s27, 0
	s_add_i32 s64, s56, s35
	global_load_lds_dwordx4 v136, s[26:27]
	s_mov_b32 m0, s64
	s_nop 0
	global_load_lds_dwordx4 v132, s[62:63]
	s_add_i32 m0, s64, 0x2000
	s_nop 0
	global_load_lds_dwordx4 v136, s[62:63]
	s_mov_b32 m0, s38
	s_nop 0
	global_load_lds_dwordx4 v130, s[28:29]
	s_mov_b32 m0, s39
	s_nop 0
	global_load_lds_dwordx4 v134, s[28:29]
	s_waitcnt vmcnt(8)
	s_waitcnt lgkmcnt(0)
	s_setprio 1
	s_barrier
	v_mfma_f32_16x16x32_bf16 v[62:65], v[152:155], v[188:191], v[62:65]
	v_mfma_f32_16x16x32_bf16 v[62:65], v[160:163], v[192:195], v[62:65]
	v_mfma_f32_16x16x32_bf16 v[58:61], v[164:167], v[188:191], v[58:61]
	v_mfma_f32_16x16x32_bf16 v[58:61], v[168:171], v[192:195], v[58:61]
	v_mfma_f32_16x16x32_bf16 v[54:57], v[172:175], v[188:191], v[54:57]
	v_mfma_f32_16x16x32_bf16 v[54:57], v[176:179], v[192:195], v[54:57]
	v_mfma_f32_16x16x32_bf16 v[50:53], v[180:183], v[188:191], v[50:53]
	v_mfma_f32_16x16x32_bf16 v[50:53], v[184:187], v[192:195], v[50:53]
	v_mfma_f32_16x16x32_bf16 v[46:49], v[152:155], v[196:199], v[46:49]
	v_mfma_f32_16x16x32_bf16 v[46:49], v[160:163], v[200:203], v[46:49]
	v_mfma_f32_16x16x32_bf16 v[42:45], v[164:167], v[196:199], v[42:45]
	v_mfma_f32_16x16x32_bf16 v[42:45], v[168:171], v[200:203], v[42:45]
	v_mfma_f32_16x16x32_bf16 v[38:41], v[172:175], v[196:199], v[38:41]
	v_mfma_f32_16x16x32_bf16 v[38:41], v[176:179], v[200:203], v[38:41]
	v_mfma_f32_16x16x32_bf16 v[34:37], v[180:183], v[196:199], v[34:37]
	v_mfma_f32_16x16x32_bf16 v[34:37], v[184:187], v[200:203], v[34:37]
	v_mfma_f32_16x16x32_bf16 v[30:33], v[152:155], v[204:207], v[30:33]
	v_mfma_f32_16x16x32_bf16 v[30:33], v[160:163], v[208:211], v[30:33]
	v_mfma_f32_16x16x32_bf16 v[26:29], v[164:167], v[204:207], v[26:29]
	v_mfma_f32_16x16x32_bf16 v[26:29], v[168:171], v[208:211], v[26:29]
	v_mfma_f32_16x16x32_bf16 v[22:25], v[172:175], v[204:207], v[22:25]
	v_mfma_f32_16x16x32_bf16 v[22:25], v[176:179], v[208:211], v[22:25]
	v_mfma_f32_16x16x32_bf16 v[18:21], v[180:183], v[204:207], v[18:21]
	v_mfma_f32_16x16x32_bf16 v[18:21], v[184:187], v[208:211], v[18:21]
	v_mfma_f32_16x16x32_bf16 v[14:17], v[152:155], v[212:215], v[14:17]
	v_mfma_f32_16x16x32_bf16 v[14:17], v[160:163], v[216:219], v[14:17]
	v_mfma_f32_16x16x32_bf16 v[10:13], v[164:167], v[212:215], v[10:13]
	v_mfma_f32_16x16x32_bf16 v[10:13], v[168:171], v[216:219], v[10:13]
	v_mfma_f32_16x16x32_bf16 v[6:9], v[172:175], v[212:215], v[6:9]
	v_mfma_f32_16x16x32_bf16 v[6:9], v[176:179], v[216:219], v[6:9]
	v_mfma_f32_16x16x32_bf16 v[2:5], v[180:183], v[212:215], v[2:5]
	v_mfma_f32_16x16x32_bf16 v[2:5], v[184:187], v[216:219], v[2:5]
	s_barrier
; #define PG8_STAGE(bufoff, gbase, voff) do { _Pragma("unroll") for (int _i = 0; _i < 2; ++_i) \
;         __builtin_amdgcn_global_load_lds((const unsigned*)((const char*)(gbase) + (voff)[_i]), (PG8_LAS unsigned*)(lds + (bufoff) + ldsw + _i * 8192), 16, 0, 0); } while (0)
; #define PG8_LDA(dst, b, h) do { _Pragma("unroll") for (int m = 0; m < 4; ++m) _Pragma("unroll") for (int k = 0; k < 2; ++k) dst[m][k] = *(const PG8_LAS bf16x8*)(lds + PG8_SA(b, h) + aoff + m * 2048 + k * 1024); } while (0)
; #define PG8_LDB(dst, b, h) do { _Pragma("unroll") for (int n = 0; n < 2; ++n) _Pragma("unroll") for (int k = 0; k < 2; ++k) dst[n][k] = *(const PG8_LAS bf16x8*)(lds + PG8_SB(b, h) + boff + n * 2048 + k * 1024); } while (0)
; #define PG8_MMA(ai, bj, At, Bt) do { __builtin_amdgcn_s_setprio(1); _Pragma("unroll") for (int m = 0; m < 4; ++m) _Pragma("unroll") for (int n = 0; n < 2; ++n) _Pragma("unroll") for (int k = 0; k < 2; ++k) \
;         acc[ai][bj][m][n] = __builtin_amdgcn_mfma_f32_16x16x32_bf16(Bt[n][k], At[m][k], acc[ai][bj][m][n], 0, 0, 0); __builtin_amdgcn_s_setprio(0); } while (0)
; #define PG8_WAIT_V(n) asm volatile("s_waitcnt vmcnt(" #n ")" ::: "memory")
; #define PG8_WAIT_L(n) asm volatile("s_waitcnt lgkmcnt(" #n ")" ::: "memory")
; #define PG8_BAR __builtin_amdgcn_s_barrier()
; #define PG8_SCHED __builtin_amdgcn_sched_barrier(0)
; template <class Epi, class Sched, bool ALIGN_EPI = false, bool SP2 = false, bool A_TILED = false>
; __device__ __forceinline__ void gemm_phase(PG8_LAS unsigned char* lds, const Gemm g, const Sched& S, const Epi& E) {
;     ...
;             PG8_WAIT_V(8); PG8_WAIT_L(0); PG8_BAR; PG8_MMA(1, 0, At, B0); PG8_MMA(1, 1, At, B1); PG8_BAR; PG8_SCHED;
;             PG8_LDB(B0, 1, 0); PG8_LDB(B1, 1, 1); PG8_SCHED; PG8_LDA(At, 1, 0); PG8_STAGE(PG8_SA(0, 1), a2 + hstepA, voffA);
;             PG8_WAIT_V(8); PG8_WAIT_L(0); PG8_BAR; PG8_MMA(0, 0, At, B0); PG8_MMA(0, 1, At, B1); PG8_BAR; PG8_SCHED;
;             PG8_LDA(At, 1, 1); PG8_STAGE(PG8_SB(1, 0), b3, voffB); PG8_STAGE(PG8_SB(1, 1), b3 + hstepB, voffB); PG8_STAGE(PG8_SA(1, 0), a3, voffA);
;             PG8_WAIT_V(8); PG8_WAIT_L(0); PG8_BAR; PG8_MMA(1, 0, At, B0); PG8_MMA(1, 1, At, B1); PG8_BAR; PG8_SCHED;
;     ...
;         if constexpr (ALIGN_EPI) { if (wr == 0) PG8_BAR; }
	s_setprio 0
	s_add_i32 s62, 0, 0x18000
	s_add_i32 s63, 0, 0x1c000
	ds_read_b128 v[152:155], v141 offset:32768
	ds_read_b128 v[160:163], v141 offset:33792
	ds_read_b128 v[164:167], v141 offset:34816
	ds_read_b128 v[168:171], v141 offset:35840
	ds_read_b128 v[172:175], v141 offset:49152
	ds_read_b128 v[176:179], v141 offset:50176
	ds_read_b128 v[180:183], v141 offset:51200
	ds_read_b128 v[184:187], v141 offset:52224
	s_add_u32 s28, s28, 0x4000
	s_addc_u32 s29, s29, 0
	s_mov_b32 m0, s40
	ds_read_b128 v[188:191], v157 offset:32768
	ds_read_b128 v[192:195], v157 offset:33792
	ds_read_b128 v[196:199], v157 offset:34816
	ds_read_b128 v[200:203], v157 offset:35840
	ds_read_b128 v[204:207], v157 offset:36864
	ds_read_b128 v[208:211], v157 offset:37888
	ds_read_b128 v[212:215], v157 offset:38912
	ds_read_b128 v[216:219], v157 offset:39936
	global_load_lds_dwordx4 v130, s[28:29]
	s_mov_b32 m0, s41
	s_nop 0
	global_load_lds_dwordx4 v134, s[28:29]
	s_waitcnt vmcnt(8)
	s_waitcnt lgkmcnt(0)
	s_setprio 1
	s_barrier
	v_mfma_f32_16x16x32_bf16 v[126:129], v[152:155], v[188:191], v[126:129]
	v_mfma_f32_16x16x32_bf16 v[126:129], v[160:163], v[192:195], v[126:129]
	v_mfma_f32_16x16x32_bf16 v[122:125], v[164:167], v[188:191], v[122:125]
	v_mfma_f32_16x16x32_bf16 v[122:125], v[168:171], v[192:195], v[122:125]
	v_mfma_f32_16x16x32_bf16 v[118:121], v[172:175], v[188:191], v[118:121]
	v_mfma_f32_16x16x32_bf16 v[118:121], v[176:179], v[192:195], v[118:121]
	v_mfma_f32_16x16x32_bf16 v[114:117], v[180:183], v[188:191], v[114:117]
	v_mfma_f32_16x16x32_bf16 v[114:117], v[184:187], v[192:195], v[114:117]
	v_mfma_f32_16x16x32_bf16 v[110:113], v[152:155], v[196:199], v[110:113]
	v_mfma_f32_16x16x32_bf16 v[110:113], v[160:163], v[200:203], v[110:113]
	v_mfma_f32_16x16x32_bf16 v[106:109], v[164:167], v[196:199], v[106:109]
	v_mfma_f32_16x16x32_bf16 v[106:109], v[168:171], v[200:203], v[106:109]
	v_mfma_f32_16x16x32_bf16 v[102:105], v[172:175], v[196:199], v[102:105]
	v_mfma_f32_16x16x32_bf16 v[102:105], v[176:179], v[200:203], v[102:105]
	v_mfma_f32_16x16x32_bf16 v[98:101], v[180:183], v[196:199], v[98:101]
	v_mfma_f32_16x16x32_bf16 v[98:101], v[184:187], v[200:203], v[98:101]
	v_mfma_f32_16x16x32_bf16 v[94:97], v[152:155], v[204:207], v[94:97]
	v_mfma_f32_16x16x32_bf16 v[94:97], v[160:163], v[208:211], v[94:97]
	v_mfma_f32_16x16x32_bf16 v[90:93], v[164:167], v[204:207], v[90:93]
	v_mfma_f32_16x16x32_bf16 v[90:93], v[168:171], v[208:211], v[90:93]
	v_mfma_f32_16x16x32_bf16 v[86:89], v[172:175], v[204:207], v[86:89]
	v_mfma_f32_16x16x32_bf16 v[86:89], v[176:179], v[208:211], v[86:89]
	v_mfma_f32_16x16x32_bf16 v[82:85], v[180:183], v[204:207], v[82:85]
	v_mfma_f32_16x16x32_bf16 v[82:85], v[184:187], v[208:211], v[82:85]
	v_mfma_f32_16x16x32_bf16 v[78:81], v[152:155], v[212:215], v[78:81]
	v_mfma_f32_16x16x32_bf16 v[78:81], v[160:163], v[216:219], v[78:81]
	v_mfma_f32_16x16x32_bf16 v[74:77], v[164:167], v[212:215], v[74:77]
	v_mfma_f32_16x16x32_bf16 v[74:77], v[168:171], v[216:219], v[74:77]
	v_mfma_f32_16x16x32_bf16 v[70:73], v[172:175], v[212:215], v[70:73]
	v_mfma_f32_16x16x32_bf16 v[70:73], v[176:179], v[216:219], v[70:73]
	v_mfma_f32_16x16x32_bf16 v[66:69], v[180:183], v[212:215], v[66:69]
	v_mfma_f32_16x16x32_bf16 v[66:69], v[184:187], v[216:219], v[66:69]
	s_barrier
	s_setprio 0
	s_add_u32 s28, s26, 0x8000
	s_addc_u32 s29, s27, 0
	s_add_i32 s62, s62, s35
	s_mov_b32 m0, s62
	ds_read_b128 v[188:191], v157 offset:49152
	ds_read_b128 v[192:195], v157 offset:50176
	ds_read_b128 v[196:199], v157 offset:51200
	ds_read_b128 v[200:203], v157 offset:52224
	ds_read_b128 v[204:207], v157 offset:53248
	ds_read_b128 v[208:211], v157 offset:54272
	ds_read_b128 v[212:215], v157 offset:55296
	ds_read_b128 v[216:219], v157 offset:56320
	global_load_lds_dwordx4 v132, s[28:29]
	s_add_i32 m0, s62, 0x2000
	s_add_u32 s26, s26, 0xc000
	v_lshl_add_u64 v[220:221], s[28:29], 0, v[136:137]
	s_addc_u32 s27, s27, 0
	s_add_i32 s28, s63, s35
	global_load_lds_dwordx4 v[220:221], off
	s_mov_b32 m0, s28
	s_nop 0
	global_load_lds_dwordx4 v132, s[26:27]
	s_add_i32 m0, s28, 0x2000
	s_nop 0
	global_load_lds_dwordx4 v136, s[26:27]
	s_mov_b32 m0, s45
	s_nop 0
	global_load_lds_dwordx4 v130, s[24:25]
	s_mov_b32 m0, s54
	s_nop 0
	global_load_lds_dwordx4 v134, s[24:25]
	s_waitcnt vmcnt(8)
	s_waitcnt lgkmcnt(0)
	s_setprio 1
	s_barrier
	v_mfma_f32_16x16x32_bf16 v[62:65], v[152:155], v[188:191], v[62:65]
	v_mfma_f32_16x16x32_bf16 v[62:65], v[160:163], v[192:195], v[62:65]
	v_mfma_f32_16x16x32_bf16 v[58:61], v[164:167], v[188:191], v[58:61]
	v_mfma_f32_16x16x32_bf16 v[58:61], v[168:171], v[192:195], v[58:61]
	v_mfma_f32_16x16x32_bf16 v[54:57], v[172:175], v[188:191], v[54:57]
	v_mfma_f32_16x16x32_bf16 v[54:57], v[176:179], v[192:195], v[54:57]
	v_mfma_f32_16x16x32_bf16 v[50:53], v[180:183], v[188:191], v[50:53]
	v_mfma_f32_16x16x32_bf16 v[50:53], v[184:187], v[192:195], v[50:53]
	v_mfma_f32_16x16x32_bf16 v[46:49], v[152:155], v[196:199], v[46:49]
	v_mfma_f32_16x16x32_bf16 v[46:49], v[160:163], v[200:203], v[46:49]
	v_mfma_f32_16x16x32_bf16 v[42:45], v[164:167], v[196:199], v[42:45]
	v_mfma_f32_16x16x32_bf16 v[42:45], v[168:171], v[200:203], v[42:45]
	v_mfma_f32_16x16x32_bf16 v[38:41], v[172:175], v[196:199], v[38:41]
	v_mfma_f32_16x16x32_bf16 v[38:41], v[176:179], v[200:203], v[38:41]
	v_mfma_f32_16x16x32_bf16 v[34:37], v[180:183], v[196:199], v[34:37]
	v_mfma_f32_16x16x32_bf16 v[34:37], v[184:187], v[200:203], v[34:37]
	v_mfma_f32_16x16x32_bf16 v[30:33], v[152:155], v[204:207], v[30:33]
	v_mfma_f32_16x16x32_bf16 v[30:33], v[160:163], v[208:211], v[30:33]
	v_mfma_f32_16x16x32_bf16 v[26:29], v[164:167], v[204:207], v[26:29]
	v_mfma_f32_16x16x32_bf16 v[26:29], v[168:171], v[208:211], v[26:29]
	v_mfma_f32_16x16x32_bf16 v[22:25], v[172:175], v[204:207], v[22:25]
	v_mfma_f32_16x16x32_bf16 v[22:25], v[176:179], v[208:211], v[22:25]
	v_mfma_f32_16x16x32_bf16 v[18:21], v[180:183], v[204:207], v[18:21]
	v_mfma_f32_16x16x32_bf16 v[18:21], v[184:187], v[208:211], v[18:21]
	v_mfma_f32_16x16x32_bf16 v[14:17], v[152:155], v[212:215], v[14:17]
	v_mfma_f32_16x16x32_bf16 v[14:17], v[160:163], v[216:219], v[14:17]
	v_mfma_f32_16x16x32_bf16 v[10:13], v[164:167], v[212:215], v[10:13]
	v_mfma_f32_16x16x32_bf16 v[10:13], v[168:171], v[216:219], v[10:13]
	v_mfma_f32_16x16x32_bf16 v[6:9], v[172:175], v[212:215], v[6:9]
	v_mfma_f32_16x16x32_bf16 v[6:9], v[176:179], v[216:219], v[6:9]
	v_mfma_f32_16x16x32_bf16 v[2:5], v[180:183], v[212:215], v[2:5]
	v_mfma_f32_16x16x32_bf16 v[2:5], v[184:187], v[216:219], v[2:5]
	s_barrier
	s_setprio 0
	s_add_i32 s61, s61, 2
	s_add_u32 s22, s22, 0x10000
	s_addc_u32 s23, s23, 0
	s_add_u32 s59, s59, 0x10000
	s_addc_u32 s60, s60, 0
	s_cmp_gt_u32 s61, 61
	s_cbranch_scc0 .LBB0_1172
	s_and_b64 vcc, exec, s[12:13]
	s_cbranch_vccz .LBB0_1175
	s_barrier

; #define PG8_STAGE(bufoff, gbase, voff) do { _Pragma("unroll") for (int _i = 0; _i < 2; ++_i) \
;         __builtin_amdgcn_global_load_lds((const unsigned*)((const char*)(gbase) + (voff)[_i]), (PG8_LAS unsigned*)(lds + (bufoff) + ldsw + _i * 8192), 16, 0, 0); } while (0)
; #define PG8_LDA(dst, b, h) do { _Pragma("unroll") for (int m = 0; m < 4; ++m) _Pragma("unroll") for (int k = 0; k < 2; ++k) dst[m][k] = *(const PG8_LAS bf16x8*)(lds + PG8_SA(b, h) + aoff + m * 2048 + k * 1024); } while (0)
; #define PG8_LDB(dst, b, h) do { _Pragma("unroll") for (int n = 0; n < 2; ++n) _Pragma("unroll") for (int k = 0; k < 2; ++k) dst[n][k] = *(const PG8_LAS bf16x8*)(lds + PG8_SB(b, h) + boff + n * 2048 + k * 1024); } while (0)
; #define PG8_WAIT_V(n) asm volatile("s_waitcnt vmcnt(" #n ")" ::: "memory")
; #define PG8_BAR __builtin_amdgcn_s_barrier()
; template <class Epi, class Sched, bool ALIGN_EPI = false, bool SP2 = false, bool A_TILED = false>
; __device__ __forceinline__ void gemm_phase(PG8_LAS unsigned char* lds, const Gemm g, const Sched& S, const Epi& E) {
;     ...
;         const bool has_next = S.next(ui + 1, nxt);
;         const char* nA = has_next ? (const char*)g.A + (size_t)nxt.pm * tstepA : cA; const char* nB = has_next ? (const char*)g.Bt + (size_t)nxt.pn * tstepB : cB;
;         for (int t = 0; t < nt; t += 2) {
;             const bool last = (t == nt - 2);
;             const char* a1 = cA + (size_t)(t + 1) * kstepA;
;             const char* a2 = last ? nA : cA + (size_t)(t + 2) * kstepA; const char* b2 = last ? nB : cB + (size_t)(t + 2) * kstepB;
;             const char* a3 = a2 + kstepA; const char* b3 = b2 + kstepB;
;             if (last && has_next) S.a_ready(nxt);
;             if constexpr (SP2) {
;             PG8_LDB(B0, 0, 0); PG8_LDB(B1, 0, 1); PG8_SCHED; PG8_LDA(At, 0, 0); PG8_STAGE(PG8_SA(1, 1), a1 + hstepA, voffA);
;             PG8_WAIT_V(8); PG8_WAIT_L(0); PG8_BAR; PG8_MMA(0, 0, At, B0); PG8_MMA(0, 1, At, B1); PG8_BAR; PG8_SCHED;
;             PG8_LDA(At, 0, 1); PG8_STAGE(PG8_SB(0, 0), b2, voffB); PG8_STAGE(PG8_SB(0, 1), b2 + hstepB, voffB); PG8_STAGE(PG8_SA(0, 0), a2, voffA);
;             PG8_WAIT_V(8); PG8_WAIT_L(0); PG8_BAR; PG8_MMA(1, 0, At, B0); PG8_MMA(1, 1, At, B1); PG8_BAR; PG8_SCHED;
;             PG8_LDB(B0, 1, 0); PG8_LDB(B1, 1, 1); PG8_SCHED; PG8_LDA(At, 1, 0); PG8_STAGE(PG8_SA(0, 1), a2 + hstepA, voffA);
.LBB0_1246:
	s_add_u32 s22, s22, 0xc000
	s_addc_u32 s23, s23, 0
	s_add_u32 s56, s24, 0x10000
	v_mov_b32_e32 v2, 0
	s_addc_u32 s57, s25, 0
	s_mov_b32 s58, -2
	ds_read_b128 v[142:145], v156
	ds_read_b128 v[146:149], v156 offset:1024
	ds_read_b128 v[150:153], v156 offset:2048
	ds_read_b128 v[160:163], v156 offset:3072
	ds_read_b128 v[164:167], v157
	ds_read_b128 v[168:171], v157 offset:1024
	ds_read_b128 v[172:175], v157 offset:2048
	ds_read_b128 v[176:179], v157 offset:3072
	s_add_u32 s24, s22, 0x4000
	s_addc_u32 s25, s23, 0
	s_cmpk_eq_i32 s58, 0xa8
	s_cselect_b32 s28, s4, s24
	s_cselect_b32 s29, s5, s25
	s_cselect_b32 s26, s20, s56
	s_cselect_b32 s27, s21, s57
	s_add_u32 s24, s28, 0x8000
	s_addc_u32 s25, s29, 0
	s_add_i32 m0, s35, 0xc000
	ds_read_b128 v[180:183], v158
	ds_read_b128 v[184:187], v158 offset:1024
	ds_read_b128 v[188:191], v158 offset:2048
	ds_read_b128 v[192:195], v158 offset:3072
	ds_read_b128 v[196:199], v158 offset:4096
	ds_read_b128 v[200:203], v158 offset:5120
	ds_read_b128 v[204:207], v158 offset:6144
	ds_read_b128 v[208:211], v158 offset:7168
	global_load_lds_dwordx4 v134, s[22:23]
	s_add_i32 m0, s35, 0xe000
	s_nop 0
	global_load_lds_dwordx4 v136, s[22:23]
	s_waitcnt vmcnt(8)
	s_waitcnt lgkmcnt(0)
	s_setprio 1
	s_barrier
	v_mfma_f32_16x16x32_bf16 v[126:129], v[142:145], v[180:183], 0
	v_mfma_f32_16x16x32_bf16 v[126:129], v[146:149], v[184:187], v[126:129]
	v_mfma_f32_16x16x32_bf16 v[122:125], v[150:153], v[180:183], 0
	v_mfma_f32_16x16x32_bf16 v[122:125], v[160:163], v[184:187], v[122:125]
	v_mfma_f32_16x16x32_bf16 v[118:121], v[142:145], v[188:191], 0
	v_mfma_f32_16x16x32_bf16 v[118:121], v[146:149], v[192:195], v[118:121]
	v_mfma_f32_16x16x32_bf16 v[114:117], v[150:153], v[188:191], 0
	v_mfma_f32_16x16x32_bf16 v[114:117], v[160:163], v[192:195], v[114:117]
	v_mfma_f32_16x16x32_bf16 v[94:97], v[142:145], v[196:199], 0
	v_mfma_f32_16x16x32_bf16 v[94:97], v[146:149], v[200:203], v[94:97]
	v_mfma_f32_16x16x32_bf16 v[90:93], v[150:153], v[196:199], 0
	v_mfma_f32_16x16x32_bf16 v[90:93], v[160:163], v[200:203], v[90:93]
	v_mfma_f32_16x16x32_bf16 v[86:89], v[142:145], v[204:207], 0
	v_mfma_f32_16x16x32_bf16 v[86:89], v[146:149], v[208:211], v[86:89]
	v_mfma_f32_16x16x32_bf16 v[82:85], v[150:153], v[204:207], 0
	v_mfma_f32_16x16x32_bf16 v[82:85], v[160:163], v[208:211], v[82:85]
	v_mfma_f32_16x16x32_bf16 v[110:113], v[164:167], v[180:183], 0
	v_mfma_f32_16x16x32_bf16 v[110:113], v[168:171], v[184:187], v[110:113]
	v_mfma_f32_16x16x32_bf16 v[106:109], v[172:175], v[180:183], 0
	v_mfma_f32_16x16x32_bf16 v[106:109], v[176:179], v[184:187], v[106:109]
	v_mfma_f32_16x16x32_bf16 v[102:105], v[164:167], v[188:191], 0
	v_mfma_f32_16x16x32_bf16 v[102:105], v[168:171], v[192:195], v[102:105]
	v_mfma_f32_16x16x32_bf16 v[98:101], v[172:175], v[188:191], 0
	v_mfma_f32_16x16x32_bf16 v[98:101], v[176:179], v[192:195], v[98:101]
	v_mfma_f32_16x16x32_bf16 v[78:81], v[164:167], v[196:199], 0
	v_mfma_f32_16x16x32_bf16 v[78:81], v[168:171], v[200:203], v[78:81]
	v_mfma_f32_16x16x32_bf16 v[74:77], v[172:175], v[196:199], 0
	v_mfma_f32_16x16x32_bf16 v[74:77], v[176:179], v[200:203], v[74:77]
	v_mfma_f32_16x16x32_bf16 v[70:73], v[164:167], v[204:207], 0
	v_mfma_f32_16x16x32_bf16 v[70:73], v[168:171], v[208:211], v[70:73]
	v_mfma_f32_16x16x32_bf16 v[66:69], v[172:175], v[204:207], 0
	v_mfma_f32_16x16x32_bf16 v[66:69], v[176:179], v[208:211], v[66:69]
	s_barrier
	s_setprio 0
	s_add_i32 s59, s42, s31
	s_mov_b32 m0, s59
	ds_read_b128 v[180:183], v158 offset:16384
	ds_read_b128 v[184:187], v158 offset:17408
	ds_read_b128 v[188:191], v158 offset:18432
	ds_read_b128 v[192:195], v158 offset:19456
	ds_read_b128 v[196:199], v158 offset:20480
	ds_read_b128 v[200:203], v158 offset:21504
	ds_read_b128 v[204:207], v158 offset:22528
	ds_read_b128 v[208:211], v158 offset:23552
	global_load_lds_dwordx4 v130, s[26:27]
	s_add_i32 m0, s59, 0x2000
	s_add_u32 s60, s26, 0x4000
	s_addc_u32 s61, s27, 0
	s_add_i32 s59, s43, s31
	global_load_lds_dwordx4 v132, s[26:27]
	s_mov_b32 m0, s59
	s_nop 0
	global_load_lds_dwordx4 v130, s[60:61]
	s_add_i32 m0, s59, 0x2000
	s_nop 0
	global_load_lds_dwordx4 v132, s[60:61]
	s_mov_b32 m0, s35
	s_nop 0
	global_load_lds_dwordx4 v130, s[28:29]
	s_mov_b32 m0, s36
	s_nop 0
	global_load_lds_dwordx4 v132, s[28:29]
	s_waitcnt vmcnt(8)
	s_waitcnt lgkmcnt(0)
	s_setprio 1
	s_barrier
	v_mfma_f32_16x16x32_bf16 v[62:65], v[142:145], v[180:183], 0
	v_mfma_f32_16x16x32_bf16 v[62:65], v[146:149], v[184:187], v[62:65]
	v_mfma_f32_16x16x32_bf16 v[58:61], v[150:153], v[180:183], 0
	v_mfma_f32_16x16x32_bf16 v[58:61], v[160:163], v[184:187], v[58:61]
	v_mfma_f32_16x16x32_bf16 v[50:53], v[164:167], v[180:183], 0
	v_mfma_f32_16x16x32_bf16 v[50:53], v[168:171], v[184:187], v[50:53]
	v_mfma_f32_16x16x32_bf16 v[42:45], v[172:175], v[180:183], 0
	v_mfma_f32_16x16x32_bf16 v[42:45], v[176:179], v[184:187], v[42:45]
	v_mfma_f32_16x16x32_bf16 v[54:57], v[142:145], v[188:191], 0
	v_mfma_f32_16x16x32_bf16 v[54:57], v[146:149], v[192:195], v[54:57]
	v_mfma_f32_16x16x32_bf16 v[46:49], v[150:153], v[188:191], 0
	v_mfma_f32_16x16x32_bf16 v[46:49], v[160:163], v[192:195], v[46:49]
	v_mfma_f32_16x16x32_bf16 v[34:37], v[164:167], v[188:191], 0
	v_mfma_f32_16x16x32_bf16 v[34:37], v[168:171], v[192:195], v[34:37]
	v_mfma_f32_16x16x32_bf16 v[26:29], v[172:175], v[188:191], 0
	v_mfma_f32_16x16x32_bf16 v[26:29], v[176:179], v[192:195], v[26:29]
	v_mfma_f32_16x16x32_bf16 v[38:41], v[142:145], v[196:199], 0
	v_mfma_f32_16x16x32_bf16 v[38:41], v[146:149], v[200:203], v[38:41]
	v_mfma_f32_16x16x32_bf16 v[30:33], v[150:153], v[196:199], 0
	v_mfma_f32_16x16x32_bf16 v[30:33], v[160:163], v[200:203], v[30:33]
	v_mfma_f32_16x16x32_bf16 v[18:21], v[164:167], v[196:199], 0
	v_mfma_f32_16x16x32_bf16 v[18:21], v[168:171], v[200:203], v[18:21]
	v_mfma_f32_16x16x32_bf16 v[10:13], v[172:175], v[196:199], 0
	v_mfma_f32_16x16x32_bf16 v[10:13], v[176:179], v[200:203], v[10:13]
	v_mfma_f32_16x16x32_bf16 v[22:25], v[142:145], v[204:207], 0
	v_mfma_f32_16x16x32_bf16 v[22:25], v[146:149], v[208:211], v[22:25]
	v_mfma_f32_16x16x32_bf16 v[14:17], v[150:153], v[204:207], 0
	v_mfma_f32_16x16x32_bf16 v[14:17], v[160:163], v[208:211], v[14:17]
	v_mfma_f32_16x16x32_bf16 v[6:9], v[164:167], v[204:207], 0
	v_mfma_f32_16x16x32_bf16 v[6:9], v[168:171], v[208:211], v[6:9]
	v_mfma_f32_16x16x32_bf16 v[2:5], v[172:175], v[204:207], 0
	v_mfma_f32_16x16x32_bf16 v[2:5], v[176:179], v[208:211], v[2:5]
	s_barrier
; #define PG8_STAGE(bufoff, gbase, voff) do { _Pragma("unroll") for (int _i = 0; _i < 2; ++_i) \
;         __builtin_amdgcn_global_load_lds((const unsigned*)((const char*)(gbase) + (voff)[_i]), (PG8_LAS unsigned*)(lds + (bufoff) + ldsw + _i * 8192), 16, 0, 0); } while (0)
; #define PG8_LDA(dst, b, h) do { _Pragma("unroll") for (int m = 0; m < 4; ++m) _Pragma("unroll") for (int k = 0; k < 2; ++k) dst[m][k] = *(const PG8_LAS bf16x8*)(lds + PG8_SA(b, h) + aoff + m * 2048 + k * 1024); } while (0)
; #define PG8_LDB(dst, b, h) do { _Pragma("unroll") for (int n = 0; n < 2; ++n) _Pragma("unroll") for (int k = 0; k < 2; ++k) dst[n][k] = *(const PG8_LAS bf16x8*)(lds + PG8_SB(b, h) + boff + n * 2048 + k * 1024); } while (0)
; #define PG8_MMA(ai, bj, At, Bt) do { __builtin_amdgcn_s_setprio(1); _Pragma("unroll") for (int m = 0; m < 4; ++m) _Pragma("unroll") for (int n = 0; n < 2; ++n) _Pragma("unroll") for (int k = 0; k < 2; ++k) \
;         acc[ai][bj][m][n] = __builtin_amdgcn_mfma_f32_16x16x32_bf16(Bt[n][k], At[m][k], acc[ai][bj][m][n], 0, 0, 0); __builtin_amdgcn_s_setprio(0); } while (0)
; #define PG8_WAIT_V(n) asm volatile("s_waitcnt vmcnt(" #n ")" ::: "memory")
; #define PG8_WAIT_L(n) asm volatile("s_waitcnt lgkmcnt(" #n ")" ::: "memory")
; #define PG8_BAR __builtin_amdgcn_s_barrier()
; #define PG8_SCHED __builtin_amdgcn_sched_barrier(0)
; template <class Epi, class Sched, bool ALIGN_EPI = false, bool SP2 = false, bool A_TILED = false>
; __device__ __forceinline__ void gemm_phase(PG8_LAS unsigned char* lds, const Gemm g, const Sched& S, const Epi& E) {
;     ...
;             PG8_WAIT_V(8); PG8_WAIT_L(0); PG8_BAR; PG8_MMA(1, 0, At, B0); PG8_MMA(1, 1, At, B1); PG8_BAR; PG8_SCHED;
;             PG8_LDB(B0, 1, 0); PG8_LDB(B1, 1, 1); PG8_SCHED; PG8_LDA(At, 1, 0); PG8_STAGE(PG8_SA(0, 1), a2 + hstepA, voffA);
;             PG8_WAIT_V(8); PG8_WAIT_L(0); PG8_BAR; PG8_MMA(0, 0, At, B0); PG8_MMA(0, 1, At, B1); PG8_BAR; PG8_SCHED;
;             PG8_LDA(At, 1, 1); PG8_STAGE(PG8_SB(1, 0), b3, voffB); PG8_STAGE(PG8_SB(1, 1), b3 + hstepB, voffB); PG8_STAGE(PG8_SA(1, 0), a3, voffA);
;             PG8_WAIT_V(8); PG8_WAIT_L(0); PG8_BAR; PG8_MMA(1, 0, At, B0); PG8_MMA(1, 1, At, B1); PG8_BAR; PG8_SCHED;
	s_setprio 0
	s_add_i32 s59, 0, 0x18000
	s_add_i32 s60, 0, 0x1c000
	ds_read_b128 v[142:145], v156 offset:32768
	ds_read_b128 v[146:149], v156 offset:33792
	ds_read_b128 v[150:153], v156 offset:34816
	ds_read_b128 v[160:163], v156 offset:35840
	ds_read_b128 v[164:167], v156 offset:49152
	ds_read_b128 v[168:171], v156 offset:50176
	ds_read_b128 v[172:175], v156 offset:51200
	ds_read_b128 v[176:179], v156 offset:52224
	s_add_u32 s28, s28, 0x4000
	s_addc_u32 s29, s29, 0
	s_mov_b32 m0, s37
	ds_read_b128 v[180:183], v158 offset:32768
	ds_read_b128 v[184:187], v158 offset:33792
	ds_read_b128 v[188:191], v158 offset:34816
	ds_read_b128 v[192:195], v158 offset:35840
	ds_read_b128 v[196:199], v158 offset:36864
	ds_read_b128 v[200:203], v158 offset:37888
	ds_read_b128 v[204:207], v158 offset:38912
	ds_read_b128 v[208:211], v158 offset:39936
	global_load_lds_dwordx4 v130, s[28:29]
	s_mov_b32 m0, s38
	s_nop 0
	global_load_lds_dwordx4 v132, s[28:29]
	s_waitcnt vmcnt(8)
	s_waitcnt lgkmcnt(0)
	s_setprio 1
	s_barrier
	v_mfma_f32_16x16x32_bf16 v[126:129], v[142:145], v[180:183], v[126:129]
	v_mfma_f32_16x16x32_bf16 v[126:129], v[146:149], v[184:187], v[126:129]
	v_mfma_f32_16x16x32_bf16 v[122:125], v[150:153], v[180:183], v[122:125]
	v_mfma_f32_16x16x32_bf16 v[122:125], v[160:163], v[184:187], v[122:125]
	v_mfma_f32_16x16x32_bf16 v[110:113], v[164:167], v[180:183], v[110:113]
	v_mfma_f32_16x16x32_bf16 v[110:113], v[168:171], v[184:187], v[110:113]
	v_mfma_f32_16x16x32_bf16 v[106:109], v[172:175], v[180:183], v[106:109]
	v_mfma_f32_16x16x32_bf16 v[106:109], v[176:179], v[184:187], v[106:109]
	v_mfma_f32_16x16x32_bf16 v[118:121], v[142:145], v[188:191], v[118:121]
	v_mfma_f32_16x16x32_bf16 v[118:121], v[146:149], v[192:195], v[118:121]
	v_mfma_f32_16x16x32_bf16 v[114:117], v[150:153], v[188:191], v[114:117]
	v_mfma_f32_16x16x32_bf16 v[114:117], v[160:163], v[192:195], v[114:117]
	v_mfma_f32_16x16x32_bf16 v[102:105], v[164:167], v[188:191], v[102:105]
	v_mfma_f32_16x16x32_bf16 v[102:105], v[168:171], v[192:195], v[102:105]
	v_mfma_f32_16x16x32_bf16 v[98:101], v[172:175], v[188:191], v[98:101]
	v_mfma_f32_16x16x32_bf16 v[98:101], v[176:179], v[192:195], v[98:101]
	v_mfma_f32_16x16x32_bf16 v[94:97], v[142:145], v[196:199], v[94:97]
	v_mfma_f32_16x16x32_bf16 v[94:97], v[146:149], v[200:203], v[94:97]
	v_mfma_f32_16x16x32_bf16 v[90:93], v[150:153], v[196:199], v[90:93]
	v_mfma_f32_16x16x32_bf16 v[90:93], v[160:163], v[200:203], v[90:93]
	v_mfma_f32_16x16x32_bf16 v[78:81], v[164:167], v[196:199], v[78:81]
	v_mfma_f32_16x16x32_bf16 v[78:81], v[168:171], v[200:203], v[78:81]
	v_mfma_f32_16x16x32_bf16 v[74:77], v[172:175], v[196:199], v[74:77]
	v_mfma_f32_16x16x32_bf16 v[74:77], v[176:179], v[200:203], v[74:77]
	v_mfma_f32_16x16x32_bf16 v[86:89], v[142:145], v[204:207], v[86:89]
	v_mfma_f32_16x16x32_bf16 v[86:89], v[146:149], v[208:211], v[86:89]
	v_mfma_f32_16x16x32_bf16 v[82:85], v[150:153], v[204:207], v[82:85]
	v_mfma_f32_16x16x32_bf16 v[82:85], v[160:163], v[208:211], v[82:85]
	v_mfma_f32_16x16x32_bf16 v[70:73], v[164:167], v[204:207], v[70:73]
	v_mfma_f32_16x16x32_bf16 v[70:73], v[168:171], v[208:211], v[70:73]
	v_mfma_f32_16x16x32_bf16 v[66:69], v[172:175], v[204:207], v[66:69]
	v_mfma_f32_16x16x32_bf16 v[66:69], v[176:179], v[208:211], v[66:69]
	s_barrier
	s_setprio 0
	s_add_u32 s28, s26, 0x8000
	s_addc_u32 s29, s27, 0
	s_add_i32 s59, s59, s31
	s_mov_b32 m0, s59
	ds_read_b128 v[180:183], v158 offset:49152
	ds_read_b128 v[184:187], v158 offset:50176
	ds_read_b128 v[188:191], v158 offset:51200
	ds_read_b128 v[192:195], v158 offset:52224
	ds_read_b128 v[196:199], v158 offset:53248
	ds_read_b128 v[200:203], v158 offset:54272
	ds_read_b128 v[204:207], v158 offset:55296
	ds_read_b128 v[208:211], v158 offset:56320
	global_load_lds_dwordx4 v130, s[28:29]
	s_add_i32 m0, s59, 0x2000
	s_add_u32 s26, s26, 0xc000
	v_lshl_add_u64 v[212:213], s[28:29], 0, v[132:133]
	s_addc_u32 s27, s27, 0
	s_add_i32 s28, s60, s31
	global_load_lds_dwordx4 v[212:213], off
	s_mov_b32 m0, s28
	s_nop 0
	global_load_lds_dwordx4 v130, s[26:27]
	s_add_i32 m0, s28, 0x2000
	s_nop 0
	global_load_lds_dwordx4 v132, s[26:27]
	s_mov_b32 m0, s40
	s_nop 0
	global_load_lds_dwordx4 v130, s[24:25]
	s_mov_b32 m0, s41
	s_nop 0
	global_load_lds_dwordx4 v132, s[24:25]
	s_waitcnt vmcnt(8)
	s_waitcnt lgkmcnt(0)
	s_setprio 1
	s_barrier
	v_mfma_f32_16x16x32_bf16 v[62:65], v[142:145], v[180:183], v[62:65]
	v_mfma_f32_16x16x32_bf16 v[62:65], v[146:149], v[184:187], v[62:65]
	v_mfma_f32_16x16x32_bf16 v[58:61], v[150:153], v[180:183], v[58:61]
	v_mfma_f32_16x16x32_bf16 v[58:61], v[160:163], v[184:187], v[58:61]
	v_mfma_f32_16x16x32_bf16 v[50:53], v[164:167], v[180:183], v[50:53]
	v_mfma_f32_16x16x32_bf16 v[50:53], v[168:171], v[184:187], v[50:53]
	v_mfma_f32_16x16x32_bf16 v[42:45], v[172:175], v[180:183], v[42:45]
	v_mfma_f32_16x16x32_bf16 v[42:45], v[176:179], v[184:187], v[42:45]
	v_mfma_f32_16x16x32_bf16 v[54:57], v[142:145], v[188:191], v[54:57]
	v_mfma_f32_16x16x32_bf16 v[54:57], v[146:149], v[192:195], v[54:57]
	v_mfma_f32_16x16x32_bf16 v[46:49], v[150:153], v[188:191], v[46:49]
	v_mfma_f32_16x16x32_bf16 v[46:49], v[160:163], v[192:195], v[46:49]
	v_mfma_f32_16x16x32_bf16 v[34:37], v[164:167], v[188:191], v[34:37]
	v_mfma_f32_16x16x32_bf16 v[34:37], v[168:171], v[192:195], v[34:37]
	v_mfma_f32_16x16x32_bf16 v[26:29], v[172:175], v[188:191], v[26:29]
	v_mfma_f32_16x16x32_bf16 v[26:29], v[176:179], v[192:195], v[26:29]
	v_mfma_f32_16x16x32_bf16 v[38:41], v[142:145], v[196:199], v[38:41]
	v_mfma_f32_16x16x32_bf16 v[38:41], v[146:149], v[200:203], v[38:41]
	v_mfma_f32_16x16x32_bf16 v[30:33], v[150:153], v[196:199], v[30:33]
	v_mfma_f32_16x16x32_bf16 v[30:33], v[160:163], v[200:203], v[30:33]
	v_mfma_f32_16x16x32_bf16 v[18:21], v[164:167], v[196:199], v[18:21]
	v_mfma_f32_16x16x32_bf16 v[18:21], v[168:171], v[200:203], v[18:21]
	v_mfma_f32_16x16x32_bf16 v[10:13], v[172:175], v[196:199], v[10:13]
	v_mfma_f32_16x16x32_bf16 v[10:13], v[176:179], v[200:203], v[10:13]
	v_mfma_f32_16x16x32_bf16 v[22:25], v[142:145], v[204:207], v[22:25]
	v_mfma_f32_16x16x32_bf16 v[22:25], v[146:149], v[208:211], v[22:25]
	v_mfma_f32_16x16x32_bf16 v[14:17], v[150:153], v[204:207], v[14:17]
	v_mfma_f32_16x16x32_bf16 v[14:17], v[160:163], v[208:211], v[14:17]
	v_mfma_f32_16x16x32_bf16 v[6:9], v[164:167], v[204:207], v[6:9]
	v_mfma_f32_16x16x32_bf16 v[6:9], v[168:171], v[208:211], v[6:9]
	v_mfma_f32_16x16x32_bf16 v[2:5], v[172:175], v[204:207], v[2:5]
	v_mfma_f32_16x16x32_bf16 v[2:5], v[176:179], v[208:211], v[2:5]
	s_barrier
	s_setprio 0
	s_add_i32 s58, s58, 2
	s_add_u32 s22, s22, 0x10000
	s_addc_u32 s23, s23, 0
	s_add_u32 s56, s56, 0x10000
	s_addc_u32 s57, s57, 0
; #define PG8_STAGE(bufoff, gbase, voff) do { _Pragma("unroll") for (int _i = 0; _i < 2; ++_i) \
;         __builtin_amdgcn_global_load_lds((const unsigned*)((const char*)(gbase) + (voff)[_i]), (PG8_LAS unsigned*)(lds + (bufoff) + ldsw + _i * 8192), 16, 0, 0); } while (0)
; #define PG8_LDA(dst, b, h) do { _Pragma("unroll") for (int m = 0; m < 4; ++m) _Pragma("unroll") for (int k = 0; k < 2; ++k) dst[m][k] = *(const PG8_LAS bf16x8*)(lds + PG8_SA(b, h) + aoff + m * 2048 + k * 1024); } while (0)
; #define PG8_LDB(dst, b, h) do { _Pragma("unroll") for (int n = 0; n < 2; ++n) _Pragma("unroll") for (int k = 0; k < 2; ++k) dst[n][k] = *(const PG8_LAS bf16x8*)(lds + PG8_SB(b, h) + boff + n * 2048 + k * 1024); } while (0)
; #define PG8_WAIT_V(n) asm volatile("s_waitcnt vmcnt(" #n ")" ::: "memory")
; #define PG8_WAIT_L(n) asm volatile("s_waitcnt lgkmcnt(" #n ")" ::: "memory")
; #define PG8_BAR __builtin_amdgcn_s_barrier()
; template <class Epi, class Sched, bool ALIGN_EPI = false, bool SP2 = false, bool A_TILED = false>
; __device__ __forceinline__ void gemm_phase(PG8_LAS unsigned char* lds, const Gemm g, const Sched& S, const Epi& E) {
;     ...
;         for (int t = 0; t < nt; t += 2) {
;             const bool last = (t == nt - 2);
;             const char* a1 = cA + (size_t)(t + 1) * kstepA;
;             const char* a2 = last ? nA : cA + (size_t)(t + 2) * kstepA; const char* b2 = last ? nB : cB + (size_t)(t + 2) * kstepB;
;             const char* a3 = a2 + kstepA; const char* b3 = b2 + kstepB;
;             if (last && has_next) S.a_ready(nxt);
;             if constexpr (SP2) {
;             PG8_LDB(B0, 0, 0); PG8_LDB(B1, 0, 1); PG8_SCHED; PG8_LDA(At, 0, 0); PG8_STAGE(PG8_SA(1, 1), a1 + hstepA, voffA);
;             PG8_WAIT_V(8); PG8_WAIT_L(0); PG8_BAR; PG8_MMA(0, 0, At, B0); PG8_MMA(0, 1, At, B1); PG8_BAR; PG8_SCHED;
;             PG8_LDA(At, 0, 1); PG8_STAGE(PG8_SB(0, 0), b2, voffB); PG8_STAGE(PG8_SB(0, 1), b2 + hstepB, voffB); PG8_STAGE(PG8_SA(0, 0), a2, voffA);
;             PG8_WAIT_V(8); PG8_WAIT_L(0); PG8_BAR; PG8_MMA(1, 0, At, B0); PG8_MMA(1, 1, At, B1); PG8_BAR; PG8_SCHED;
;             PG8_LDB(B0, 1, 0); PG8_LDB(B1, 1, 1); PG8_SCHED; PG8_LDA(At, 1, 0); PG8_STAGE(PG8_SA(0, 1), a2 + hstepA, voffA);
;             PG8_WAIT_V(8); PG8_WAIT_L(0); PG8_BAR; PG8_MMA(0, 0, At, B0); PG8_MMA(0, 1, At, B1); PG8_BAR; PG8_SCHED;
.LBB0_1247:
	ds_read_b128 v[142:145], v156
	ds_read_b128 v[146:149], v156 offset:1024
	ds_read_b128 v[150:153], v156 offset:2048
	ds_read_b128 v[160:163], v156 offset:3072
	ds_read_b128 v[164:167], v157
	ds_read_b128 v[168:171], v157 offset:1024
	ds_read_b128 v[172:175], v157 offset:2048
	ds_read_b128 v[176:179], v157 offset:3072
	s_add_u32 s24, s22, 0x4000
	s_addc_u32 s25, s23, 0
	s_cmpk_eq_i32 s58, 0xa8
	s_cselect_b32 s28, s4, s24
	s_cselect_b32 s29, s5, s25
	s_cselect_b32 s26, s20, s56
	s_cselect_b32 s27, s21, s57
	s_add_u32 s24, s28, 0x8000
	s_addc_u32 s25, s29, 0
	s_add_i32 m0, s35, 0xc000
	ds_read_b128 v[180:183], v158
	ds_read_b128 v[184:187], v158 offset:1024
	ds_read_b128 v[188:191], v158 offset:2048
	ds_read_b128 v[192:195], v158 offset:3072
	ds_read_b128 v[196:199], v158 offset:4096
	ds_read_b128 v[200:203], v158 offset:5120
	ds_read_b128 v[204:207], v158 offset:6144
	ds_read_b128 v[208:211], v158 offset:7168
	global_load_lds_dwordx4 v134, s[22:23]
	s_add_i32 m0, s35, 0xe000
	s_nop 0
	global_load_lds_dwordx4 v136, s[22:23]
	s_waitcnt vmcnt(8)
	s_waitcnt lgkmcnt(0)
	s_setprio 1
	s_barrier
	v_mfma_f32_16x16x32_bf16 v[126:129], v[142:145], v[180:183], v[126:129]
	v_mfma_f32_16x16x32_bf16 v[126:129], v[146:149], v[184:187], v[126:129]
	v_mfma_f32_16x16x32_bf16 v[122:125], v[150:153], v[180:183], v[122:125]
	v_mfma_f32_16x16x32_bf16 v[122:125], v[160:163], v[184:187], v[122:125]
	v_mfma_f32_16x16x32_bf16 v[118:121], v[142:145], v[188:191], v[118:121]
	v_mfma_f32_16x16x32_bf16 v[118:121], v[146:149], v[192:195], v[118:121]
	v_mfma_f32_16x16x32_bf16 v[114:117], v[150:153], v[188:191], v[114:117]
	v_mfma_f32_16x16x32_bf16 v[114:117], v[160:163], v[192:195], v[114:117]
	v_mfma_f32_16x16x32_bf16 v[94:97], v[142:145], v[196:199], v[94:97]
	v_mfma_f32_16x16x32_bf16 v[94:97], v[146:149], v[200:203], v[94:97]
	v_mfma_f32_16x16x32_bf16 v[90:93], v[150:153], v[196:199], v[90:93]
	v_mfma_f32_16x16x32_bf16 v[90:93], v[160:163], v[200:203], v[90:93]
	v_mfma_f32_16x16x32_bf16 v[86:89], v[142:145], v[204:207], v[86:89]
	v_mfma_f32_16x16x32_bf16 v[86:89], v[146:149], v[208:211], v[86:89]
	v_mfma_f32_16x16x32_bf16 v[82:85], v[150:153], v[204:207], v[82:85]
	v_mfma_f32_16x16x32_bf16 v[82:85], v[160:163], v[208:211], v[82:85]
	v_mfma_f32_16x16x32_bf16 v[110:113], v[164:167], v[180:183], v[110:113]
	v_mfma_f32_16x16x32_bf16 v[110:113], v[168:171], v[184:187], v[110:113]
	v_mfma_f32_16x16x32_bf16 v[106:109], v[172:175], v[180:183], v[106:109]
	v_mfma_f32_16x16x32_bf16 v[106:109], v[176:179], v[184:187], v[106:109]
	v_mfma_f32_16x16x32_bf16 v[102:105], v[164:167], v[188:191], v[102:105]
	v_mfma_f32_16x16x32_bf16 v[102:105], v[168:171], v[192:195], v[102:105]
	v_mfma_f32_16x16x32_bf16 v[98:101], v[172:175], v[188:191], v[98:101]
	v_mfma_f32_16x16x32_bf16 v[98:101], v[176:179], v[192:195], v[98:101]
	v_mfma_f32_16x16x32_bf16 v[78:81], v[164:167], v[196:199], v[78:81]
	v_mfma_f32_16x16x32_bf16 v[78:81], v[168:171], v[200:203], v[78:81]
	v_mfma_f32_16x16x32_bf16 v[74:77], v[172:175], v[196:199], v[74:77]
	v_mfma_f32_16x16x32_bf16 v[74:77], v[176:179], v[200:203], v[74:77]
	v_mfma_f32_16x16x32_bf16 v[70:73], v[164:167], v[204:207], v[70:73]
	v_mfma_f32_16x16x32_bf16 v[70:73], v[168:171], v[208:211], v[70:73]
	v_mfma_f32_16x16x32_bf16 v[66:69], v[172:175], v[204:207], v[66:69]
	v_mfma_f32_16x16x32_bf16 v[66:69], v[176:179], v[208:211], v[66:69]
	s_barrier
	s_setprio 0
	s_add_i32 s59, s42, s31
	s_mov_b32 m0, s59
	ds_read_b128 v[180:183], v158 offset:16384
	ds_read_b128 v[184:187], v158 offset:17408
	ds_read_b128 v[188:191], v158 offset:18432
	ds_read_b128 v[192:195], v158 offset:19456
	ds_read_b128 v[196:199], v158 offset:20480
	ds_read_b128 v[200:203], v158 offset:21504
	ds_read_b128 v[204:207], v158 offset:22528
	ds_read_b128 v[208:211], v158 offset:23552
	global_load_lds_dwordx4 v130, s[26:27]
	s_add_i32 m0, s59, 0x2000
	s_add_u32 s60, s26, 0x4000
	s_addc_u32 s61, s27, 0
	s_add_i32 s59, s43, s31
	global_load_lds_dwordx4 v132, s[26:27]
	s_mov_b32 m0, s59
	s_nop 0
	global_load_lds_dwordx4 v130, s[60:61]
	s_add_i32 m0, s59, 0x2000
	s_nop 0
	global_load_lds_dwordx4 v132, s[60:61]
	s_mov_b32 m0, s35
	s_nop 0
	global_load_lds_dwordx4 v130, s[28:29]
	s_mov_b32 m0, s36
	s_nop 0
	global_load_lds_dwordx4 v132, s[28:29]
	s_waitcnt vmcnt(8)
	s_waitcnt lgkmcnt(0)
	s_setprio 1
	s_barrier
	v_mfma_f32_16x16x32_bf16 v[62:65], v[142:145], v[180:183], v[62:65]
	v_mfma_f32_16x16x32_bf16 v[62:65], v[146:149], v[184:187], v[62:65]
	v_mfma_f32_16x16x32_bf16 v[58:61], v[150:153], v[180:183], v[58:61]
	v_mfma_f32_16x16x32_bf16 v[58:61], v[160:163], v[184:187], v[58:61]
	v_mfma_f32_16x16x32_bf16 v[50:53], v[164:167], v[180:183], v[50:53]
	v_mfma_f32_16x16x32_bf16 v[50:53], v[168:171], v[184:187], v[50:53]
	v_mfma_f32_16x16x32_bf16 v[42:45], v[172:175], v[180:183], v[42:45]
	v_mfma_f32_16x16x32_bf16 v[42:45], v[176:179], v[184:187], v[42:45]
	v_mfma_f32_16x16x32_bf16 v[54:57], v[142:145], v[188:191], v[54:57]
	v_mfma_f32_16x16x32_bf16 v[54:57], v[146:149], v[192:195], v[54:57]
	v_mfma_f32_16x16x32_bf16 v[46:49], v[150:153], v[188:191], v[46:49]
	v_mfma_f32_16x16x32_bf16 v[46:49], v[160:163], v[192:195], v[46:49]
	v_mfma_f32_16x16x32_bf16 v[34:37], v[164:167], v[188:191], v[34:37]
	v_mfma_f32_16x16x32_bf16 v[34:37], v[168:171], v[192:195], v[34:37]
	v_mfma_f32_16x16x32_bf16 v[26:29], v[172:175], v[188:191], v[26:29]
	v_mfma_f32_16x16x32_bf16 v[26:29], v[176:179], v[192:195], v[26:29]
	v_mfma_f32_16x16x32_bf16 v[38:41], v[142:145], v[196:199], v[38:41]
	v_mfma_f32_16x16x32_bf16 v[38:41], v[146:149], v[200:203], v[38:41]
	v_mfma_f32_16x16x32_bf16 v[30:33], v[150:153], v[196:199], v[30:33]
	v_mfma_f32_16x16x32_bf16 v[30:33], v[160:163], v[200:203], v[30:33]
	v_mfma_f32_16x16x32_bf16 v[18:21], v[164:167], v[196:199], v[18:21]
	v_mfma_f32_16x16x32_bf16 v[18:21], v[168:171], v[200:203], v[18:21]
	v_mfma_f32_16x16x32_bf16 v[10:13], v[172:175], v[196:199], v[10:13]
	v_mfma_f32_16x16x32_bf16 v[10:13], v[176:179], v[200:203], v[10:13]
	v_mfma_f32_16x16x32_bf16 v[22:25], v[142:145], v[204:207], v[22:25]
	v_mfma_f32_16x16x32_bf16 v[22:25], v[146:149], v[208:211], v[22:25]
	v_mfma_f32_16x16x32_bf16 v[14:17], v[150:153], v[204:207], v[14:17]
	v_mfma_f32_16x16x32_bf16 v[14:17], v[160:163], v[208:211], v[14:17]
	v_mfma_f32_16x16x32_bf16 v[6:9], v[164:167], v[204:207], v[6:9]
	v_mfma_f32_16x16x32_bf16 v[6:9], v[168:171], v[208:211], v[6:9]
	v_mfma_f32_16x16x32_bf16 v[2:5], v[172:175], v[204:207], v[2:5]
	v_mfma_f32_16x16x32_bf16 v[2:5], v[176:179], v[208:211], v[2:5]
	s_barrier
; #define PG8_STAGE(bufoff, gbase, voff) do { _Pragma("unroll") for (int _i = 0; _i < 2; ++_i) \
;         __builtin_amdgcn_global_load_lds((const unsigned*)((const char*)(gbase) + (voff)[_i]), (PG8_LAS unsigned*)(lds + (bufoff) + ldsw + _i * 8192), 16, 0, 0); } while (0)
; #define PG8_LDA(dst, b, h) do { _Pragma("unroll") for (int m = 0; m < 4; ++m) _Pragma("unroll") for (int k = 0; k < 2; ++k) dst[m][k] = *(const PG8_LAS bf16x8*)(lds + PG8_SA(b, h) + aoff + m * 2048 + k * 1024); } while (0)
; #define PG8_LDB(dst, b, h) do { _Pragma("unroll") for (int n = 0; n < 2; ++n) _Pragma("unroll") for (int k = 0; k < 2; ++k) dst[n][k] = *(const PG8_LAS bf16x8*)(lds + PG8_SB(b, h) + boff + n * 2048 + k * 1024); } while (0)
; #define PG8_MMA(ai, bj, At, Bt) do { __builtin_amdgcn_s_setprio(1); _Pragma("unroll") for (int m = 0; m < 4; ++m) _Pragma("unroll") for (int n = 0; n < 2; ++n) _Pragma("unroll") for (int k = 0; k < 2; ++k) \
;         acc[ai][bj][m][n] = __builtin_amdgcn_mfma_f32_16x16x32_bf16(Bt[n][k], At[m][k], acc[ai][bj][m][n], 0, 0, 0); __builtin_amdgcn_s_setprio(0); } while (0)
; #define PG8_WAIT_V(n) asm volatile("s_waitcnt vmcnt(" #n ")" ::: "memory")
; #define PG8_WAIT_L(n) asm volatile("s_waitcnt lgkmcnt(" #n ")" ::: "memory")
; #define PG8_BAR __builtin_amdgcn_s_barrier()
; #define PG8_SCHED __builtin_amdgcn_sched_barrier(0)
; template <class Epi, class Sched, bool ALIGN_EPI = false, bool SP2 = false, bool A_TILED = false>
; __device__ __forceinline__ void gemm_phase(PG8_LAS unsigned char* lds, const Gemm g, const Sched& S, const Epi& E) {
;     ...
;             PG8_WAIT_V(8); PG8_WAIT_L(0); PG8_BAR; PG8_MMA(1, 0, At, B0); PG8_MMA(1, 1, At, B1); PG8_BAR; PG8_SCHED;
;             PG8_LDB(B0, 1, 0); PG8_LDB(B1, 1, 1); PG8_SCHED; PG8_LDA(At, 1, 0); PG8_STAGE(PG8_SA(0, 1), a2 + hstepA, voffA);
;             PG8_WAIT_V(8); PG8_WAIT_L(0); PG8_BAR; PG8_MMA(0, 0, At, B0); PG8_MMA(0, 1, At, B1); PG8_BAR; PG8_SCHED;
;             PG8_LDA(At, 1, 1); PG8_STAGE(PG8_SB(1, 0), b3, voffB); PG8_STAGE(PG8_SB(1, 1), b3 + hstepB, voffB); PG8_STAGE(PG8_SA(1, 0), a3, voffA);
;             PG8_WAIT_V(8); PG8_WAIT_L(0); PG8_BAR; PG8_MMA(1, 0, At, B0); PG8_MMA(1, 1, At, B1); PG8_BAR; PG8_SCHED;
;     ...
;         if constexpr (ALIGN_EPI) { if (wr == 0) PG8_BAR; }
	s_setprio 0
	s_add_i32 s59, 0, 0x18000
	s_add_i32 s60, 0, 0x1c000
	ds_read_b128 v[142:145], v156 offset:32768
	ds_read_b128 v[146:149], v156 offset:33792
	ds_read_b128 v[150:153], v156 offset:34816
	ds_read_b128 v[160:163], v156 offset:35840
	ds_read_b128 v[164:167], v156 offset:49152
	ds_read_b128 v[168:171], v156 offset:50176
	ds_read_b128 v[172:175], v156 offset:51200
	ds_read_b128 v[176:179], v156 offset:52224
	s_add_u32 s28, s28, 0x4000
	s_addc_u32 s29, s29, 0
	s_mov_b32 m0, s37
	ds_read_b128 v[180:183], v158 offset:32768
	ds_read_b128 v[184:187], v158 offset:33792
	ds_read_b128 v[188:191], v158 offset:34816
	ds_read_b128 v[192:195], v158 offset:35840
	ds_read_b128 v[196:199], v158 offset:36864
	ds_read_b128 v[200:203], v158 offset:37888
	ds_read_b128 v[204:207], v158 offset:38912
	ds_read_b128 v[208:211], v158 offset:39936
	global_load_lds_dwordx4 v130, s[28:29]
	s_mov_b32 m0, s38
	s_nop 0
	global_load_lds_dwordx4 v132, s[28:29]
	s_waitcnt vmcnt(8)
	s_waitcnt lgkmcnt(0)
	s_setprio 1
	s_barrier
	v_mfma_f32_16x16x32_bf16 v[126:129], v[142:145], v[180:183], v[126:129]
	v_mfma_f32_16x16x32_bf16 v[126:129], v[146:149], v[184:187], v[126:129]
	v_mfma_f32_16x16x32_bf16 v[122:125], v[150:153], v[180:183], v[122:125]
	v_mfma_f32_16x16x32_bf16 v[122:125], v[160:163], v[184:187], v[122:125]
	v_mfma_f32_16x16x32_bf16 v[110:113], v[164:167], v[180:183], v[110:113]
	v_mfma_f32_16x16x32_bf16 v[110:113], v[168:171], v[184:187], v[110:113]
	v_mfma_f32_16x16x32_bf16 v[106:109], v[172:175], v[180:183], v[106:109]
	v_mfma_f32_16x16x32_bf16 v[106:109], v[176:179], v[184:187], v[106:109]
	v_mfma_f32_16x16x32_bf16 v[118:121], v[142:145], v[188:191], v[118:121]
	v_mfma_f32_16x16x32_bf16 v[118:121], v[146:149], v[192:195], v[118:121]
	v_mfma_f32_16x16x32_bf16 v[114:117], v[150:153], v[188:191], v[114:117]
	v_mfma_f32_16x16x32_bf16 v[114:117], v[160:163], v[192:195], v[114:117]
	v_mfma_f32_16x16x32_bf16 v[102:105], v[164:167], v[188:191], v[102:105]
	v_mfma_f32_16x16x32_bf16 v[102:105], v[168:171], v[192:195], v[102:105]
	v_mfma_f32_16x16x32_bf16 v[98:101], v[172:175], v[188:191], v[98:101]
	v_mfma_f32_16x16x32_bf16 v[98:101], v[176:179], v[192:195], v[98:101]
	v_mfma_f32_16x16x32_bf16 v[94:97], v[142:145], v[196:199], v[94:97]
	v_mfma_f32_16x16x32_bf16 v[94:97], v[146:149], v[200:203], v[94:97]
	v_mfma_f32_16x16x32_bf16 v[90:93], v[150:153], v[196:199], v[90:93]
	v_mfma_f32_16x16x32_bf16 v[90:93], v[160:163], v[200:203], v[90:93]
	v_mfma_f32_16x16x32_bf16 v[78:81], v[164:167], v[196:199], v[78:81]
	v_mfma_f32_16x16x32_bf16 v[78:81], v[168:171], v[200:203], v[78:81]
	v_mfma_f32_16x16x32_bf16 v[74:77], v[172:175], v[196:199], v[74:77]
	v_mfma_f32_16x16x32_bf16 v[74:77], v[176:179], v[200:203], v[74:77]
	v_mfma_f32_16x16x32_bf16 v[86:89], v[142:145], v[204:207], v[86:89]
	v_mfma_f32_16x16x32_bf16 v[86:89], v[146:149], v[208:211], v[86:89]
	v_mfma_f32_16x16x32_bf16 v[82:85], v[150:153], v[204:207], v[82:85]
	v_mfma_f32_16x16x32_bf16 v[82:85], v[160:163], v[208:211], v[82:85]
	v_mfma_f32_16x16x32_bf16 v[70:73], v[164:167], v[204:207], v[70:73]
	v_mfma_f32_16x16x32_bf16 v[70:73], v[168:171], v[208:211], v[70:73]
	v_mfma_f32_16x16x32_bf16 v[66:69], v[172:175], v[204:207], v[66:69]
	v_mfma_f32_16x16x32_bf16 v[66:69], v[176:179], v[208:211], v[66:69]
	s_barrier
	s_setprio 0
	s_add_u32 s28, s26, 0x8000
	s_addc_u32 s29, s27, 0
	s_add_i32 s59, s59, s31
	s_mov_b32 m0, s59
	ds_read_b128 v[180:183], v158 offset:49152
	ds_read_b128 v[184:187], v158 offset:50176
	ds_read_b128 v[188:191], v158 offset:51200
	ds_read_b128 v[192:195], v158 offset:52224
	ds_read_b128 v[196:199], v158 offset:53248
	ds_read_b128 v[200:203], v158 offset:54272
	ds_read_b128 v[204:207], v158 offset:55296
	ds_read_b128 v[208:211], v158 offset:56320
	global_load_lds_dwordx4 v130, s[28:29]
	s_add_i32 m0, s59, 0x2000
	s_add_u32 s26, s26, 0xc000
	v_lshl_add_u64 v[212:213], s[28:29], 0, v[132:133]
	s_addc_u32 s27, s27, 0
	s_add_i32 s28, s60, s31
	global_load_lds_dwordx4 v[212:213], off
	s_mov_b32 m0, s28
	s_nop 0
	global_load_lds_dwordx4 v130, s[26:27]
	s_add_i32 m0, s28, 0x2000
	s_nop 0
	global_load_lds_dwordx4 v132, s[26:27]
	s_mov_b32 m0, s40
	s_nop 0
	global_load_lds_dwordx4 v130, s[24:25]
	s_mov_b32 m0, s41
	s_nop 0
	global_load_lds_dwordx4 v132, s[24:25]
	s_waitcnt vmcnt(8)
	s_waitcnt lgkmcnt(0)
	s_setprio 1
	s_barrier
	v_mfma_f32_16x16x32_bf16 v[62:65], v[142:145], v[180:183], v[62:65]
	v_mfma_f32_16x16x32_bf16 v[62:65], v[146:149], v[184:187], v[62:65]
	v_mfma_f32_16x16x32_bf16 v[58:61], v[150:153], v[180:183], v[58:61]
	v_mfma_f32_16x16x32_bf16 v[58:61], v[160:163], v[184:187], v[58:61]
	v_mfma_f32_16x16x32_bf16 v[50:53], v[164:167], v[180:183], v[50:53]
	v_mfma_f32_16x16x32_bf16 v[50:53], v[168:171], v[184:187], v[50:53]
	v_mfma_f32_16x16x32_bf16 v[42:45], v[172:175], v[180:183], v[42:45]
	v_mfma_f32_16x16x32_bf16 v[42:45], v[176:179], v[184:187], v[42:45]
	v_mfma_f32_16x16x32_bf16 v[54:57], v[142:145], v[188:191], v[54:57]
	v_mfma_f32_16x16x32_bf16 v[54:57], v[146:149], v[192:195], v[54:57]
	v_mfma_f32_16x16x32_bf16 v[46:49], v[150:153], v[188:191], v[46:49]
	v_mfma_f32_16x16x32_bf16 v[46:49], v[160:163], v[192:195], v[46:49]
	v_mfma_f32_16x16x32_bf16 v[34:37], v[164:167], v[188:191], v[34:37]
	v_mfma_f32_16x16x32_bf16 v[34:37], v[168:171], v[192:195], v[34:37]
	v_mfma_f32_16x16x32_bf16 v[26:29], v[172:175], v[188:191], v[26:29]
	v_mfma_f32_16x16x32_bf16 v[26:29], v[176:179], v[192:195], v[26:29]
	v_mfma_f32_16x16x32_bf16 v[38:41], v[142:145], v[196:199], v[38:41]
	v_mfma_f32_16x16x32_bf16 v[38:41], v[146:149], v[200:203], v[38:41]
	v_mfma_f32_16x16x32_bf16 v[30:33], v[150:153], v[196:199], v[30:33]
	v_mfma_f32_16x16x32_bf16 v[30:33], v[160:163], v[200:203], v[30:33]
	v_mfma_f32_16x16x32_bf16 v[18:21], v[164:167], v[196:199], v[18:21]
	v_mfma_f32_16x16x32_bf16 v[18:21], v[168:171], v[200:203], v[18:21]
	v_mfma_f32_16x16x32_bf16 v[10:13], v[172:175], v[196:199], v[10:13]
	v_mfma_f32_16x16x32_bf16 v[10:13], v[176:179], v[200:203], v[10:13]
	v_mfma_f32_16x16x32_bf16 v[22:25], v[142:145], v[204:207], v[22:25]
	v_mfma_f32_16x16x32_bf16 v[22:25], v[146:149], v[208:211], v[22:25]
	v_mfma_f32_16x16x32_bf16 v[14:17], v[150:153], v[204:207], v[14:17]
	v_mfma_f32_16x16x32_bf16 v[14:17], v[160:163], v[208:211], v[14:17]
	v_mfma_f32_16x16x32_bf16 v[6:9], v[164:167], v[204:207], v[6:9]
	v_mfma_f32_16x16x32_bf16 v[6:9], v[168:171], v[208:211], v[6:9]
	v_mfma_f32_16x16x32_bf16 v[2:5], v[172:175], v[204:207], v[2:5]
	v_mfma_f32_16x16x32_bf16 v[2:5], v[176:179], v[208:211], v[2:5]
	s_barrier
	s_setprio 0
	s_add_i32 s58, s58, 2
	s_add_u32 s22, s22, 0x10000
	s_addc_u32 s23, s23, 0
	s_add_u32 s56, s56, 0x10000
	s_addc_u32 s57, s57, 0
	s_cmpk_gt_u32 s58, 0xa9
	s_cbranch_scc0 .LBB0_1247
	s_and_b64 vcc, exec, s[10:11]
	s_cbranch_vccz .LBB0_1250
	s_barrier
